# attention epilogues (A, B, C): pairs of 8-byte per-lane output pieces are exchanged across the lane halves (v_permlane32_swap) and stored as one 16-byte piece per lane: half the store instructions / L
# speedup vs baseline: 1.1439x; 1.0076x over previous
.LBB0_128:
	v_exp_f32_e32 v0, v66
	v_exp_f32_e32 v67, v67
	v_exp_f32_e32 v68, v68
	v_exp_f32_e32 v69, v69
	v_add_f32_e32 v66, 0, v0
	v_exp_f32_e32 v70, v70
	v_add_f32_e32 v66, v67, v66
	v_exp_f32_e32 v71, v71
	v_add_f32_e32 v66, v68, v66
	v_exp_f32_e32 v72, v72
	v_add_f32_e32 v66, v69, v66
	v_exp_f32_e32 v98, v73
	v_add_f32_e32 v66, v70, v66
	v_exp_f32_e32 v74, v74
	v_add_f32_e32 v66, v71, v66
	v_exp_f32_e32 v75, v75
	v_add_f32_e32 v66, v72, v66
	v_exp_f32_e32 v76, v76
	v_add_f32_e32 v66, v98, v66
	v_exp_f32_e32 v77, v77
	v_add_f32_e32 v66, v74, v66
	v_exp_f32_e32 v78, v78
	v_add_f32_e32 v66, v75, v66
	v_exp_f32_e32 v79, v79
	v_add_f32_e32 v66, v76, v66
	v_exp_f32_e32 v80, v80
	v_add_f32_e32 v66, v77, v66
	v_exp_f32_e32 v81, v81
	v_add_f32_e32 v66, v78, v66
	v_add_f32_e32 v66, v79, v66
	v_add_f32_e32 v66, v80, v66
	v_add_f32_e32 v66, v81, v66
	v_add_f32_e32 v73, v166, v66
	v_cvt_pk_bf16_f32 v66, v0, v67
	v_cvt_pk_bf16_f32 v67, v68, v69
	v_cvt_pk_bf16_f32 v68, v70, v71
	v_cvt_pk_bf16_f32 v69, v72, v98
	s_waitcnt vmcnt(0)
	s_barrier
	v_mbcnt_lo_u32_b32 v108, -1, 0
	v_mbcnt_hi_u32_b32 v108, -1, v108
	v_cmp_gt_u32_e32 vcc, 32, v108
	s_nop 1
	v_cndmask_b32_e64 v109, -1, 0, vcc
	v_cndmask_b32_e64 v108, -8, 16, vcc
	v_mfma_f32_32x32x16_bf16 v[18:33], v[82:85], v[66:69], v[18:33]
	v_mbcnt_lo_u32_b32 v0, -1, 0
	v_mbcnt_hi_u32_b32 v0, -1, v0
	s_movk_i32 s0, 0x100
	s_movk_i32 s5, 0xf3c0
	s_mov_b64 s[18:19], 0x44012c0
	s_mov_b32 s8, 0x4401000
	v_mfma_f32_32x32x16_bf16 v[2:17], v[86:89], v[66:69], v[2:17]
	v_cvt_pk_bf16_f32 v66, v74, v75
	v_cvt_pk_bf16_f32 v67, v76, v77
	v_cvt_pk_bf16_f32 v68, v78, v79
	v_cvt_pk_bf16_f32 v69, v80, v81
	s_nop 1
	v_mfma_f32_32x32x16_bf16 v[18:33], v[90:93], v[66:69], v[18:33]
	v_mfma_f32_32x32x16_bf16 v[2:17], v[94:97], v[66:69], v[2:17]
	v_add_u32_e32 v66, s77, v0
	v_cmp_gt_u32_e32 vcc, s0, v66
	v_mov_b32_e32 v68, s30
	v_mov_b32_e32 v69, s28
	v_cndmask_b32_e32 v68, v68, v69, vcc
	v_and_b32_e32 v66, 0xc0, v66
	v_and_b32_e32 v67, 31, v0
	v_lshl_or_b32 v66, v68, 8, v66
	v_or3_b32 v86, v66, v67, s40
	v_mov_b32_e32 v66, v142
	s_nop 1
	v_permlane32_swap_b32_e32 v142, v66
	v_add_f32_e32 v72, v142, v66
	v_mov_b64_e32 v[66:67], s[74:75]
	v_mad_u64_u32 v[66:67], s[0:1], v86, s4, v[66:67]
	v_mov_b32_e32 v68, 0x14c0
	v_mad_i32_i24 v67, s41, v68, v67
	s_lshl_b32 s28, s31, 1
	v_lshrrev_b32_e32 v0, 2, v0
	v_lshl_add_u64 v[68:69], v[66:67], 0, s[28:29]
	v_and_b32_e32 v0, 8, v0
	v_lshl_add_u64 v[68:69], v[68:69], 0, v[0:1]
	v_mad_u64_u32 v[88:89], s[0:1], v86, s5, v[66:67]
	v_mov_b32_e32 v94, 0xfffff3c0
	v_lshl_add_u64 v[90:91], v[68:69], 0, s[18:19]
	v_add_co_u32_e32 v68, vcc, s8, v68
	v_mad_i32_i24 v70, s41, v94, v89
	s_nop 0
	v_addc_co_u32_e32 v69, vcc, 0, v69, vcc
	v_sub_u32_e32 v89, v70, v86
	global_load_dwordx2 v[84:85], v[68:69], off offset:704
	global_load_dwordx2 v[82:83], v[90:91], off offset:16
	global_load_dwordx2 v[80:81], v[90:91], off offset:32
	global_load_dwordx2 v[78:79], v[90:91], off offset:48
	global_load_dwordx2 v[76:77], v[90:91], off offset:64
	global_load_dwordx2 v[74:75], v[90:91], off offset:80
	global_load_dwordx2 v[70:71], v[90:91], off offset:96
	global_load_dwordx2 v[68:69], v[90:91], off offset:112
	v_rcp_f32_e32 v72, v72
	v_lshl_add_u64 v[88:89], v[88:89], 0, s[28:29]
	s_mov_b64 s[0:1], 0x29800
	v_pk_mul_f32 v[50:51], v[50:51], v[72:73] op_sel_hi:[1,0]
	v_pk_mul_f32 v[52:53], v[52:53], v[72:73] op_sel_hi:[1,0]
	v_pk_mul_f32 v[54:55], v[54:55], v[72:73] op_sel_hi:[1,0]
	v_pk_mul_f32 v[56:57], v[56:57], v[72:73] op_sel_hi:[1,0]
	v_pk_mul_f32 v[34:35], v[34:35], v[72:73] op_sel_hi:[1,0]
	v_pk_mul_f32 v[36:37], v[36:37], v[72:73] op_sel_hi:[1,0]
	v_pk_mul_f32 v[38:39], v[38:39], v[72:73] op_sel_hi:[1,0]
	v_pk_mul_f32 v[40:41], v[40:41], v[72:73] op_sel_hi:[1,0]
	s_waitcnt vmcnt(7)
	v_lshlrev_b32_e32 v90, 16, v84
	v_and_b32_e32 v91, 0xffff0000, v84
	v_mul_f32_e32 v84, 0xbfb8aa3b, v90
	v_exp_f32_e32 v84, v84
	s_nop 0
	v_add_f32_e32 v84, 1.0, v84
	v_rcp_f32_e32 v92, v84
	v_mul_f32_e32 v84, 0xbfb8aa3b, v91
	v_exp_f32_e32 v84, v84
	s_nop 0
	v_add_f32_e32 v84, 1.0, v84
	v_rcp_f32_e32 v93, v84
	v_lshlrev_b32_e32 v84, 16, v85
	v_mul_f32_e32 v87, 0xbfb8aa3b, v84
	v_exp_f32_e32 v87, v87
	v_pk_mul_f32 v[90:91], v[92:93], v[90:91]
	v_and_b32_e32 v85, 0xffff0000, v85
	v_pk_mul_f32 v[50:51], v[50:51], v[90:91]
	v_add_f32_e32 v87, 1.0, v87
	v_rcp_f32_e32 v90, v87
	v_mul_f32_e32 v87, 0xbfb8aa3b, v85
	v_exp_f32_e32 v87, v87
	s_nop 0
	v_add_f32_e32 v87, 1.0, v87
	v_rcp_f32_e32 v91, v87
	s_nop 0
	v_pk_mul_f32 v[84:85], v[90:91], v[84:85]
	s_nop 0
	v_pk_mul_f32 v[52:53], v[52:53], v[84:85]
	v_cvt_pk_bf16_f32 v84, v50, v51
	v_cvt_pk_bf16_f32 v85, v52, v53
	s_waitcnt vmcnt(6)
	v_lshlrev_b32_e32 v52, 16, v82
	v_and_b32_e32 v53, 0xffff0000, v82
	v_mul_f32_e32 v82, 0xbfb8aa3b, v52
	v_exp_f32_e32 v82, v82
	v_lshl_add_u64 v[50:51], v[88:89], 0, v[0:1]
	v_mov_b32_e32 v106, v84
	v_mov_b32_e32 v107, v85
	v_add_f32_e32 v82, 1.0, v82
	v_rcp_f32_e32 v84, v82
	v_mul_f32_e32 v82, 0xbfb8aa3b, v53
	v_exp_f32_e32 v82, v82
	s_nop 0
	v_add_f32_e32 v82, 1.0, v82
	v_rcp_f32_e32 v85, v82
	s_nop 0
	v_pk_mul_f32 v[52:53], v[84:85], v[52:53]
	s_nop 0
	v_pk_mul_f32 v[52:53], v[54:55], v[52:53]
	v_lshlrev_b32_e32 v54, 16, v83
	v_and_b32_e32 v55, 0xffff0000, v83
	v_mul_f32_e32 v82, 0xbfb8aa3b, v54
	v_mul_f32_e32 v83, 0xbfb8aa3b, v55
	v_exp_f32_e32 v82, v82
	v_exp_f32_e32 v83, v83
	v_cvt_pk_bf16_f32 v52, v52, v53
	v_add_f32_e32 v82, 1.0, v82
	v_add_f32_e32 v83, 1.0, v83
	v_rcp_f32_e32 v82, v82
	v_rcp_f32_e32 v83, v83
	s_nop 0
	v_pk_mul_f32 v[54:55], v[82:83], v[54:55]
	s_nop 0
	v_pk_mul_f32 v[54:55], v[56:57], v[54:55]
	v_pk_mul_f32 v[56:57], v[58:59], v[72:73] op_sel_hi:[1,0]
	v_cvt_pk_bf16_f32 v53, v54, v55
	v_lshl_add_u64 v[110:111], v[50:51], 0, v[108:109]
	v_mov_b32_e32 v104, v52
	v_mov_b32_e32 v105, v53
	s_nop 1
	v_permlane32_swap_b32_e32 v104, v106
	v_permlane32_swap_b32_e32 v105, v107
	global_store_dwordx4 v[110:111], v[104:107], off offset:1536
	s_waitcnt vmcnt(6)
	v_lshlrev_b32_e32 v52, 16, v80
	v_and_b32_e32 v53, 0xffff0000, v80
	v_mul_f32_e32 v54, 0xbfb8aa3b, v52
	v_mul_f32_e32 v55, 0xbfb8aa3b, v53
	v_exp_f32_e32 v54, v54
	v_exp_f32_e32 v55, v55
	v_pk_mul_f32 v[58:59], v[60:61], v[72:73] op_sel_hi:[1,0]
	v_add_f32_e32 v54, 1.0, v54
	v_add_f32_e32 v55, 1.0, v55
	v_rcp_f32_e32 v54, v54
	v_rcp_f32_e32 v55, v55
	s_nop 0
	v_pk_mul_f32 v[52:53], v[54:55], v[52:53]
	v_lshlrev_b32_e32 v54, 16, v81
	v_and_b32_e32 v55, 0xffff0000, v81
	v_pk_mul_f32 v[52:53], v[56:57], v[52:53]
	v_mul_f32_e32 v56, 0xbfb8aa3b, v54
	v_mul_f32_e32 v57, 0xbfb8aa3b, v55
	v_exp_f32_e32 v56, v56
	v_exp_f32_e32 v57, v57
	v_cvt_pk_bf16_f32 v52, v52, v53
	v_add_f32_e32 v56, 1.0, v56
	v_add_f32_e32 v57, 1.0, v57
	v_rcp_f32_e32 v56, v56
	v_rcp_f32_e32 v57, v57
	s_nop 0
	v_pk_mul_f32 v[54:55], v[56:57], v[54:55]
	s_nop 0
	v_pk_mul_f32 v[54:55], v[58:59], v[54:55]
	v_pk_mul_f32 v[56:57], v[62:63], v[72:73] op_sel_hi:[1,0]
	v_cvt_pk_bf16_f32 v53, v54, v55
	v_mov_b32_e32 v106, v52
	v_mov_b32_e32 v107, v53
	s_waitcnt vmcnt(5)
	v_lshlrev_b32_e32 v52, 16, v78
	v_and_b32_e32 v53, 0xffff0000, v78
	v_mul_f32_e32 v54, 0xbfb8aa3b, v52
	v_mul_f32_e32 v55, 0xbfb8aa3b, v53
	v_exp_f32_e32 v54, v54
	v_exp_f32_e32 v55, v55
	v_pk_mul_f32 v[58:59], v[64:65], v[72:73] op_sel_hi:[1,0]
	v_add_f32_e32 v54, 1.0, v54
	v_add_f32_e32 v55, 1.0, v55
	v_rcp_f32_e32 v54, v54
	v_rcp_f32_e32 v55, v55
	s_nop 0
	v_pk_mul_f32 v[52:53], v[54:55], v[52:53]
	v_lshlrev_b32_e32 v54, 16, v79
	v_and_b32_e32 v55, 0xffff0000, v79
	v_pk_mul_f32 v[52:53], v[56:57], v[52:53]
	v_mul_f32_e32 v56, 0xbfb8aa3b, v54
	v_mul_f32_e32 v57, 0xbfb8aa3b, v55
	v_exp_f32_e32 v56, v56
	v_exp_f32_e32 v57, v57
	v_cvt_pk_bf16_f32 v52, v52, v53
	v_add_f32_e32 v56, 1.0, v56
	v_add_f32_e32 v57, 1.0, v57
	v_rcp_f32_e32 v56, v56
	v_rcp_f32_e32 v57, v57
	s_nop 0
	v_pk_mul_f32 v[54:55], v[56:57], v[54:55]
	s_nop 0
	v_pk_mul_f32 v[54:55], v[58:59], v[54:55]
	s_nop 0
	v_cvt_pk_bf16_f32 v53, v54, v55
	v_mov_b32_e32 v104, v52
	v_mov_b32_e32 v105, v53
	s_nop 1
	v_permlane32_swap_b32_e32 v104, v106
	v_permlane32_swap_b32_e32 v105, v107
	global_store_dwordx4 v[110:111], v[104:107], off offset:1568
	s_waitcnt vmcnt(5)
	v_lshlrev_b32_e32 v52, 16, v76
	v_and_b32_e32 v53, 0xffff0000, v76
	v_mul_f32_e32 v54, 0xbfb8aa3b, v52
	v_mul_f32_e32 v55, 0xbfb8aa3b, v53
	v_exp_f32_e32 v54, v54
	v_exp_f32_e32 v55, v55
	v_add_f32_e32 v54, 1.0, v54
	v_add_f32_e32 v55, 1.0, v55
	v_rcp_f32_e32 v54, v54
	v_rcp_f32_e32 v55, v55
	s_nop 0
	v_pk_mul_f32 v[52:53], v[54:55], v[52:53]
	s_nop 0
	v_pk_mul_f32 v[34:35], v[34:35], v[52:53]
	v_lshlrev_b32_e32 v52, 16, v77
	v_and_b32_e32 v53, 0xffff0000, v77
	v_mul_f32_e32 v54, 0xbfb8aa3b, v52
	v_mul_f32_e32 v55, 0xbfb8aa3b, v53
	v_exp_f32_e32 v54, v54
	v_exp_f32_e32 v55, v55
	v_cvt_pk_bf16_f32 v34, v34, v35
	v_add_f32_e32 v54, 1.0, v54
	v_add_f32_e32 v55, 1.0, v55
	v_rcp_f32_e32 v54, v54
	v_rcp_f32_e32 v55, v55
	s_nop 0
	v_pk_mul_f32 v[52:53], v[54:55], v[52:53]
	s_nop 0
	v_pk_mul_f32 v[36:37], v[36:37], v[52:53]
	s_nop 0
	v_cvt_pk_bf16_f32 v35, v36, v37
	v_mov_b32_e32 v106, v34
	v_mov_b32_e32 v107, v35
	s_waitcnt vmcnt(4)
	v_lshlrev_b32_e32 v34, 16, v74
	v_and_b32_e32 v35, 0xffff0000, v74
	v_mul_f32_e32 v36, 0xbfb8aa3b, v34
	v_mul_f32_e32 v37, 0xbfb8aa3b, v35
	v_exp_f32_e32 v36, v36
	v_exp_f32_e32 v37, v37
	v_add_f32_e32 v36, 1.0, v36
	v_add_f32_e32 v37, 1.0, v37
	v_rcp_f32_e32 v36, v36
	v_rcp_f32_e32 v37, v37
	s_nop 0
	v_pk_mul_f32 v[34:35], v[36:37], v[34:35]
	v_lshlrev_b32_e32 v36, 16, v75
	v_and_b32_e32 v37, 0xffff0000, v75
	v_pk_mul_f32 v[34:35], v[38:39], v[34:35]
	v_mul_f32_e32 v38, 0xbfb8aa3b, v36
	v_mul_f32_e32 v39, 0xbfb8aa3b, v37
	v_exp_f32_e32 v38, v38
	v_exp_f32_e32 v39, v39
	v_cvt_pk_bf16_f32 v34, v34, v35
	v_add_f32_e32 v38, 1.0, v38
	v_add_f32_e32 v39, 1.0, v39
	v_rcp_f32_e32 v38, v38
	v_rcp_f32_e32 v39, v39
	s_nop 0
	v_pk_mul_f32 v[36:37], v[38:39], v[36:37]
	s_nop 0
	v_pk_mul_f32 v[36:37], v[40:41], v[36:37]
	v_pk_mul_f32 v[38:39], v[42:43], v[72:73] op_sel_hi:[1,0]
	v_cvt_pk_bf16_f32 v35, v36, v37
	v_mov_b32_e32 v104, v34
	v_mov_b32_e32 v105, v35
	s_nop 1
	v_permlane32_swap_b32_e32 v104, v106
	v_permlane32_swap_b32_e32 v105, v107
	global_store_dwordx4 v[110:111], v[104:107], off offset:1600
	s_waitcnt vmcnt(4)
	v_lshlrev_b32_e32 v34, 16, v70
	v_and_b32_e32 v35, 0xffff0000, v70
	v_mul_f32_e32 v36, 0xbfb8aa3b, v34
	v_mul_f32_e32 v37, 0xbfb8aa3b, v35
	v_exp_f32_e32 v36, v36
	v_exp_f32_e32 v37, v37
	v_pk_mul_f32 v[40:41], v[44:45], v[72:73] op_sel_hi:[1,0]
	v_add_f32_e32 v36, 1.0, v36
	v_add_f32_e32 v37, 1.0, v37
	v_rcp_f32_e32 v36, v36
	v_rcp_f32_e32 v37, v37
	s_nop 0
	v_pk_mul_f32 v[34:35], v[36:37], v[34:35]
	v_lshlrev_b32_e32 v36, 16, v71
	v_and_b32_e32 v37, 0xffff0000, v71
	v_pk_mul_f32 v[34:35], v[38:39], v[34:35]
	v_mul_f32_e32 v38, 0xbfb8aa3b, v36
	v_mul_f32_e32 v39, 0xbfb8aa3b, v37
	v_exp_f32_e32 v38, v38
	v_exp_f32_e32 v39, v39
	v_cvt_pk_bf16_f32 v34, v34, v35
	v_add_f32_e32 v38, 1.0, v38
	v_add_f32_e32 v39, 1.0, v39
	v_rcp_f32_e32 v38, v38
	v_rcp_f32_e32 v39, v39
	s_nop 0
	v_pk_mul_f32 v[36:37], v[38:39], v[36:37]
	s_nop 0
	v_pk_mul_f32 v[36:37], v[40:41], v[36:37]
	v_pk_mul_f32 v[38:39], v[46:47], v[72:73] op_sel_hi:[1,0]
	v_cvt_pk_bf16_f32 v35, v36, v37
	v_mov_b32_e32 v106, v34
	v_mov_b32_e32 v107, v35
	s_waitcnt vmcnt(3)
	v_lshlrev_b32_e32 v34, 16, v68
	v_and_b32_e32 v35, 0xffff0000, v68
	v_mul_f32_e32 v36, 0xbfb8aa3b, v34
	v_mul_f32_e32 v37, 0xbfb8aa3b, v35
	v_exp_f32_e32 v36, v36
	v_exp_f32_e32 v37, v37
	v_pk_mul_f32 v[40:41], v[48:49], v[72:73] op_sel_hi:[1,0]
	v_add_f32_e32 v36, 1.0, v36
	v_add_f32_e32 v37, 1.0, v37
	v_rcp_f32_e32 v36, v36
	v_rcp_f32_e32 v37, v37
	s_nop 0
	v_pk_mul_f32 v[34:35], v[36:37], v[34:35]
	v_lshlrev_b32_e32 v36, 16, v69
	v_and_b32_e32 v37, 0xffff0000, v69
	v_pk_mul_f32 v[34:35], v[38:39], v[34:35]
	v_mul_f32_e32 v38, 0xbfb8aa3b, v36
	v_mul_f32_e32 v39, 0xbfb8aa3b, v37
	v_exp_f32_e32 v38, v38
	v_exp_f32_e32 v39, v39
	v_cvt_pk_bf16_f32 v34, v34, v35
	v_add_f32_e32 v38, 1.0, v38
	v_add_f32_e32 v39, 1.0, v39
	v_rcp_f32_e32 v38, v38
	v_rcp_f32_e32 v39, v39
	s_nop 0
	v_pk_mul_f32 v[36:37], v[38:39], v[36:37]
	s_nop 0
	v_pk_mul_f32 v[36:37], v[40:41], v[36:37]
	v_or_b32_e32 v38, 32, v86
	v_cvt_pk_bf16_f32 v35, v36, v37
	v_mov_b32_e32 v104, v34
	v_mov_b32_e32 v105, v35
	s_nop 1
	v_permlane32_swap_b32_e32 v104, v106
	v_permlane32_swap_b32_e32 v105, v107
	global_store_dwordx4 v[110:111], v[104:107], off offset:1632
	v_mov_b32_e32 v34, v73
	s_nop 1
	v_permlane32_swap_b32_e32 v73, v34
	v_add_f32_e32 v54, v73, v34
	v_lshl_add_u64 v[34:35], v[66:67], 0, s[0:1]
	v_lshl_add_u64 v[36:37], v[34:35], 0, s[28:29]
	v_mad_u64_u32 v[52:53], s[0:1], v38, s5, v[34:35]
	v_mad_i32_i24 v34, s41, v94, v53
	v_lshl_add_u64 v[36:37], v[36:37], 0, v[0:1]
	v_sub_u32_e32 v53, v34, v38
	v_lshl_add_u64 v[34:35], v[36:37], 0, s[18:19]
	v_add_co_u32_e32 v36, vcc, s8, v36
	v_lshl_add_u64 v[52:53], v[52:53], 0, s[28:29]
	s_nop 0
	v_addc_co_u32_e32 v37, vcc, 0, v37, vcc
	global_load_dwordx2 v[50:51], v[36:37], off offset:704
	global_load_dwordx2 v[48:49], v[34:35], off offset:16
	global_load_dwordx2 v[46:47], v[34:35], off offset:32
	global_load_dwordx2 v[44:45], v[34:35], off offset:48
	global_load_dwordx2 v[42:43], v[34:35], off offset:64
	global_load_dwordx2 v[40:41], v[34:35], off offset:80
	global_load_dwordx2 v[38:39], v[34:35], off offset:96
	global_load_dwordx2 v[36:37], v[34:35], off offset:112
	v_rcp_f32_e32 v34, v54
	s_waitcnt vmcnt(7)
	v_lshlrev_b32_e32 v54, 16, v50
	v_mul_f32_e32 v35, 0xbfb8aa3b, v54
	v_exp_f32_e32 v35, v35
	v_and_b32_e32 v55, 0xffff0000, v50
	v_lshlrev_b32_e32 v50, 16, v51
	v_and_b32_e32 v51, 0xffff0000, v51
	v_add_f32_e32 v35, 1.0, v35
	v_rcp_f32_e32 v56, v35
	v_pk_mul_f32 v[18:19], v[18:19], v[34:35] op_sel_hi:[1,0]
	v_mul_f32_e32 v35, 0xbfb8aa3b, v55
	v_exp_f32_e32 v35, v35
	s_nop 0
	v_add_f32_e32 v35, 1.0, v35
	v_rcp_f32_e32 v57, v35
	v_mul_f32_e32 v35, 0xbfb8aa3b, v50
	v_exp_f32_e32 v35, v35
	v_pk_mul_f32 v[54:55], v[56:57], v[54:55]
	s_nop 0
	v_pk_mul_f32 v[18:19], v[18:19], v[54:55]
	v_add_f32_e32 v35, 1.0, v35
	v_rcp_f32_e32 v54, v35
	v_pk_mul_f32 v[20:21], v[20:21], v[34:35] op_sel_hi:[1,0]
	v_mul_f32_e32 v35, 0xbfb8aa3b, v51
	v_exp_f32_e32 v35, v35
	s_nop 0
	v_add_f32_e32 v35, 1.0, v35
	v_rcp_f32_e32 v55, v35
	v_pk_mul_f32 v[22:23], v[22:23], v[34:35] op_sel_hi:[1,0]
	v_pk_mul_f32 v[24:25], v[24:25], v[34:35] op_sel_hi:[1,0]
	v_pk_mul_f32 v[2:3], v[2:3], v[34:35] op_sel_hi:[1,0]
	v_pk_mul_f32 v[50:51], v[54:55], v[50:51]
	v_pk_mul_f32 v[4:5], v[4:5], v[34:35] op_sel_hi:[1,0]
	v_pk_mul_f32 v[20:21], v[20:21], v[50:51]
	v_cvt_pk_bf16_f32 v50, v18, v19
	v_cvt_pk_bf16_f32 v51, v20, v21
	s_waitcnt vmcnt(6)
	v_lshlrev_b32_e32 v20, 16, v48
	v_lshl_add_u64 v[18:19], v[52:53], 0, v[0:1]
	v_mul_f32_e32 v0, 0xbfb8aa3b, v20
	v_exp_f32_e32 v0, v0
	v_and_b32_e32 v21, 0xffff0000, v48
	v_mov_b32_e32 v106, v50
	v_mov_b32_e32 v107, v51
	v_pk_mul_f32 v[6:7], v[6:7], v[34:35] op_sel_hi:[1,0]
	v_add_f32_e32 v0, 1.0, v0
	v_rcp_f32_e32 v50, v0
	v_mul_f32_e32 v0, 0xbfb8aa3b, v21
	v_exp_f32_e32 v0, v0
	v_pk_mul_f32 v[8:9], v[8:9], v[34:35] op_sel_hi:[1,0]
	v_add_f32_e32 v0, 1.0, v0
	v_rcp_f32_e32 v51, v0
	s_nop 0
	v_pk_mul_f32 v[20:21], v[50:51], v[20:21]
	s_nop 0
	v_pk_mul_f32 v[20:21], v[22:23], v[20:21]
	v_lshlrev_b32_e32 v22, 16, v49
	v_mul_f32_e32 v0, 0xbfb8aa3b, v22
	v_exp_f32_e32 v0, v0
	v_and_b32_e32 v23, 0xffff0000, v49
	v_cvt_pk_bf16_f32 v20, v20, v21
	v_add_f32_e32 v0, 1.0, v0
	v_rcp_f32_e32 v48, v0
	v_mul_f32_e32 v0, 0xbfb8aa3b, v23
	v_exp_f32_e32 v0, v0
	s_nop 0
	v_add_f32_e32 v0, 1.0, v0
	v_rcp_f32_e32 v49, v0
	s_nop 0
	v_pk_mul_f32 v[22:23], v[48:49], v[22:23]
	s_nop 0
	v_pk_mul_f32 v[22:23], v[24:25], v[22:23]
	v_pk_mul_f32 v[24:25], v[26:27], v[34:35] op_sel_hi:[1,0]
	v_cvt_pk_bf16_f32 v21, v22, v23
	v_lshl_add_u64 v[112:113], v[18:19], 0, v[108:109]
	v_mov_b32_e32 v104, v20
	v_mov_b32_e32 v105, v21
	s_nop 1
	v_permlane32_swap_b32_e32 v104, v106
	v_permlane32_swap_b32_e32 v105, v107
	global_store_dwordx4 v[112:113], v[104:107], off offset:1536
	s_waitcnt vmcnt(6)
	v_lshlrev_b32_e32 v20, 16, v46
	v_mul_f32_e32 v0, 0xbfb8aa3b, v20
	v_exp_f32_e32 v0, v0
	v_and_b32_e32 v21, 0xffff0000, v46
	v_pk_mul_f32 v[26:27], v[28:29], v[34:35] op_sel_hi:[1,0]
	v_add_f32_e32 v0, 1.0, v0
	v_rcp_f32_e32 v22, v0
	v_mul_f32_e32 v0, 0xbfb8aa3b, v21
	v_exp_f32_e32 v0, v0
	s_nop 0
	v_add_f32_e32 v0, 1.0, v0
	v_rcp_f32_e32 v23, v0
	s_nop 0
	v_pk_mul_f32 v[20:21], v[22:23], v[20:21]
	v_lshlrev_b32_e32 v22, 16, v47
	v_mul_f32_e32 v0, 0xbfb8aa3b, v22
	v_exp_f32_e32 v0, v0
	v_and_b32_e32 v23, 0xffff0000, v47
	v_pk_mul_f32 v[20:21], v[24:25], v[20:21]
	v_add_f32_e32 v0, 1.0, v0
	v_rcp_f32_e32 v24, v0
	v_mul_f32_e32 v0, 0xbfb8aa3b, v23
	v_exp_f32_e32 v0, v0
	v_cvt_pk_bf16_f32 v20, v20, v21
	v_add_f32_e32 v0, 1.0, v0
	v_rcp_f32_e32 v25, v0
	s_nop 0
	v_pk_mul_f32 v[22:23], v[24:25], v[22:23]
	s_nop 0
	v_pk_mul_f32 v[22:23], v[26:27], v[22:23]
	v_pk_mul_f32 v[24:25], v[30:31], v[34:35] op_sel_hi:[1,0]
	v_cvt_pk_bf16_f32 v21, v22, v23
	v_mov_b32_e32 v106, v20
	v_mov_b32_e32 v107, v21
	s_waitcnt vmcnt(5)
	v_lshlrev_b32_e32 v20, 16, v44
	v_mul_f32_e32 v0, 0xbfb8aa3b, v20
	v_exp_f32_e32 v0, v0
	v_and_b32_e32 v21, 0xffff0000, v44
	v_pk_mul_f32 v[26:27], v[32:33], v[34:35] op_sel_hi:[1,0]
	v_add_f32_e32 v0, 1.0, v0
	v_rcp_f32_e32 v22, v0
	v_mul_f32_e32 v0, 0xbfb8aa3b, v21
	v_exp_f32_e32 v0, v0
	s_nop 0
	v_add_f32_e32 v0, 1.0, v0
	v_rcp_f32_e32 v23, v0
	s_nop 0
	v_pk_mul_f32 v[20:21], v[22:23], v[20:21]
	v_lshlrev_b32_e32 v22, 16, v45
	v_mul_f32_e32 v0, 0xbfb8aa3b, v22
	v_exp_f32_e32 v0, v0
	v_and_b32_e32 v23, 0xffff0000, v45
	v_pk_mul_f32 v[20:21], v[24:25], v[20:21]
	v_add_f32_e32 v0, 1.0, v0
	v_rcp_f32_e32 v24, v0
	v_mul_f32_e32 v0, 0xbfb8aa3b, v23
	v_exp_f32_e32 v0, v0
	v_cvt_pk_bf16_f32 v20, v20, v21
	v_add_f32_e32 v0, 1.0, v0
	v_rcp_f32_e32 v25, v0
	s_nop 0
	v_pk_mul_f32 v[22:23], v[24:25], v[22:23]
	s_nop 0
	v_pk_mul_f32 v[22:23], v[26:27], v[22:23]
	s_nop 0
	v_cvt_pk_bf16_f32 v21, v22, v23
	v_mov_b32_e32 v104, v20
	v_mov_b32_e32 v105, v21
	s_nop 1
	v_permlane32_swap_b32_e32 v104, v106
	v_permlane32_swap_b32_e32 v105, v107
	global_store_dwordx4 v[112:113], v[104:107], off offset:1568
	s_waitcnt vmcnt(5)
	v_lshlrev_b32_e32 v20, 16, v42
	v_mul_f32_e32 v0, 0xbfb8aa3b, v20
	v_exp_f32_e32 v0, v0
	v_and_b32_e32 v21, 0xffff0000, v42
	v_add_f32_e32 v0, 1.0, v0
	v_rcp_f32_e32 v22, v0
	v_mul_f32_e32 v0, 0xbfb8aa3b, v21
	v_exp_f32_e32 v0, v0
	s_nop 0
	v_add_f32_e32 v0, 1.0, v0
	v_rcp_f32_e32 v23, v0
	s_nop 0
	v_pk_mul_f32 v[20:21], v[22:23], v[20:21]
	s_nop 0
	v_pk_mul_f32 v[2:3], v[2:3], v[20:21]
	v_lshlrev_b32_e32 v20, 16, v43
	v_mul_f32_e32 v0, 0xbfb8aa3b, v20
	v_exp_f32_e32 v0, v0
	v_and_b32_e32 v21, 0xffff0000, v43
	v_cvt_pk_bf16_f32 v2, v2, v3
	v_add_f32_e32 v0, 1.0, v0
	v_rcp_f32_e32 v22, v0
	v_mul_f32_e32 v0, 0xbfb8aa3b, v21
	v_exp_f32_e32 v0, v0
	s_nop 0
	v_add_f32_e32 v0, 1.0, v0
	v_rcp_f32_e32 v23, v0
	s_nop 0
	v_pk_mul_f32 v[20:21], v[22:23], v[20:21]
	s_nop 0
	v_pk_mul_f32 v[4:5], v[4:5], v[20:21]
	s_nop 0
	v_cvt_pk_bf16_f32 v3, v4, v5
	v_mov_b32_e32 v106, v2
	v_mov_b32_e32 v107, v3
	s_waitcnt vmcnt(4)
	v_lshlrev_b32_e32 v2, 16, v40
	v_mul_f32_e32 v0, 0xbfb8aa3b, v2
	v_exp_f32_e32 v0, v0
	v_and_b32_e32 v3, 0xffff0000, v40
	v_add_f32_e32 v0, 1.0, v0
	v_rcp_f32_e32 v4, v0
	v_mul_f32_e32 v0, 0xbfb8aa3b, v3
	v_exp_f32_e32 v0, v0
	s_nop 0
	v_add_f32_e32 v0, 1.0, v0
	v_rcp_f32_e32 v5, v0
	s_nop 0
	v_pk_mul_f32 v[2:3], v[4:5], v[2:3]
	v_lshlrev_b32_e32 v4, 16, v41
	v_mul_f32_e32 v0, 0xbfb8aa3b, v4
	v_exp_f32_e32 v0, v0
	v_and_b32_e32 v5, 0xffff0000, v41
	v_pk_mul_f32 v[2:3], v[6:7], v[2:3]
	v_add_f32_e32 v0, 1.0, v0
	v_rcp_f32_e32 v6, v0
	v_mul_f32_e32 v0, 0xbfb8aa3b, v5
	v_exp_f32_e32 v0, v0
	v_cvt_pk_bf16_f32 v2, v2, v3
	v_add_f32_e32 v0, 1.0, v0
	v_rcp_f32_e32 v7, v0
	s_nop 0
	v_pk_mul_f32 v[4:5], v[6:7], v[4:5]
	s_nop 0
	v_pk_mul_f32 v[4:5], v[8:9], v[4:5]
	v_pk_mul_f32 v[6:7], v[10:11], v[34:35] op_sel_hi:[1,0]
	v_cvt_pk_bf16_f32 v3, v4, v5
	v_mov_b32_e32 v104, v2
	v_mov_b32_e32 v105, v3
	s_nop 1
	v_permlane32_swap_b32_e32 v104, v106
	v_permlane32_swap_b32_e32 v105, v107
	global_store_dwordx4 v[112:113], v[104:107], off offset:1600
	s_waitcnt vmcnt(4)
	v_lshlrev_b32_e32 v2, 16, v38
	v_mul_f32_e32 v0, 0xbfb8aa3b, v2
	v_exp_f32_e32 v0, v0
	v_and_b32_e32 v3, 0xffff0000, v38
	v_pk_mul_f32 v[8:9], v[12:13], v[34:35] op_sel_hi:[1,0]
	v_add_f32_e32 v0, 1.0, v0
	v_rcp_f32_e32 v4, v0
	v_mul_f32_e32 v0, 0xbfb8aa3b, v3
	v_exp_f32_e32 v0, v0
	s_nop 0
	v_add_f32_e32 v0, 1.0, v0
	v_rcp_f32_e32 v5, v0
	s_nop 0
	v_pk_mul_f32 v[2:3], v[4:5], v[2:3]
	v_lshlrev_b32_e32 v4, 16, v39
	v_mul_f32_e32 v0, 0xbfb8aa3b, v4
	v_exp_f32_e32 v0, v0
	v_and_b32_e32 v5, 0xffff0000, v39
	v_pk_mul_f32 v[2:3], v[6:7], v[2:3]
	v_add_f32_e32 v0, 1.0, v0
	v_rcp_f32_e32 v6, v0
	v_mul_f32_e32 v0, 0xbfb8aa3b, v5
	v_exp_f32_e32 v0, v0
	v_cvt_pk_bf16_f32 v2, v2, v3
	v_add_f32_e32 v0, 1.0, v0
	v_rcp_f32_e32 v7, v0
	s_nop 0
	v_pk_mul_f32 v[4:5], v[6:7], v[4:5]
	s_nop 0
	v_pk_mul_f32 v[4:5], v[8:9], v[4:5]
	v_pk_mul_f32 v[6:7], v[14:15], v[34:35] op_sel_hi:[1,0]
	v_cvt_pk_bf16_f32 v3, v4, v5
	v_mov_b32_e32 v106, v2
	v_mov_b32_e32 v107, v3
	s_waitcnt vmcnt(3)
	v_lshlrev_b32_e32 v2, 16, v36
	v_mul_f32_e32 v0, 0xbfb8aa3b, v2
	v_exp_f32_e32 v0, v0
	v_and_b32_e32 v3, 0xffff0000, v36
	v_pk_mul_f32 v[8:9], v[16:17], v[34:35] op_sel_hi:[1,0]
	v_add_f32_e32 v0, 1.0, v0
	v_rcp_f32_e32 v4, v0
	v_mul_f32_e32 v0, 0xbfb8aa3b, v3
	v_exp_f32_e32 v0, v0
	s_nop 0
	v_add_f32_e32 v0, 1.0, v0
	v_rcp_f32_e32 v5, v0
	s_nop 0
	v_pk_mul_f32 v[2:3], v[4:5], v[2:3]
	v_lshlrev_b32_e32 v4, 16, v37
	v_mul_f32_e32 v0, 0xbfb8aa3b, v4
	v_exp_f32_e32 v0, v0
	v_and_b32_e32 v5, 0xffff0000, v37
	v_pk_mul_f32 v[2:3], v[6:7], v[2:3]
	v_add_f32_e32 v0, 1.0, v0
	v_rcp_f32_e32 v6, v0
	v_mul_f32_e32 v0, 0xbfb8aa3b, v5
	v_exp_f32_e32 v0, v0
	v_cvt_pk_bf16_f32 v2, v2, v3
	v_add_f32_e32 v0, 1.0, v0
	v_rcp_f32_e32 v7, v0
	s_nop 0
	v_pk_mul_f32 v[4:5], v[6:7], v[4:5]
	s_nop 0
	v_pk_mul_f32 v[4:5], v[8:9], v[4:5]
	s_nop 0
	v_cvt_pk_bf16_f32 v3, v4, v5
	v_mov_b32_e32 v104, v2
	v_mov_b32_e32 v105, v3
	s_nop 1
	v_permlane32_swap_b32_e32 v104, v106
	v_permlane32_swap_b32_e32 v105, v107
	global_store_dwordx4 v[112:113], v[104:107], off offset:1632

.LBB0_175:
	s_waitcnt vmcnt(0) lgkmcnt(0)
	s_barrier
	v_mbcnt_lo_u32_b32 v108, -1, 0
	v_mbcnt_hi_u32_b32 v108, -1, v108
	v_cmp_gt_u32_e32 vcc, 32, v108
	s_nop 1
	v_cndmask_b32_e64 v109, -1, 0, vcc
	v_cndmask_b32_e64 v108, -8, 16, vcc
	v_mbcnt_lo_u32_b32 v72, -1, 0
	v_mbcnt_hi_u32_b32 v72, -1, v72
	s_movk_i32 s0, 0x100
	v_add_u32_e32 v0, s77, v72
	v_cmp_gt_u32_e32 vcc, s0, v0
	v_mov_b32_e32 v66, s20
	v_mov_b32_e32 v67, s9
	v_cndmask_b32_e32 v70, v66, v67, vcc
	v_mov_b32_e32 v66, s43
	v_mov_b32_e32 v67, s21
	v_cndmask_b32_e32 v66, v66, v67, vcc
	v_and_b32_e32 v0, 0xc0, v0
	v_lshl_or_b32 v0, v66, 8, v0
	v_add_u32_e32 v0, s45, v0
	v_and_or_b32 v75, v72, 31, v0
	v_mov_b32_e32 v0, v151
	s_nop 1
	v_permlane32_swap_b32_e32 v151, v0
	v_mov_b64_e32 v[66:67], s[74:75]
	v_add_f32_e32 v74, v151, v0
	v_mad_u64_u32 v[68:69], s[0:1], v75, s4, v[66:67]
	v_lshlrev_b32_e32 v0, 7, v70
	v_lshrrev_b32_e32 v66, 2, v72
	v_lshl_add_u64 v[70:71], v[68:69], 0, v[0:1]
	v_and_b32_e32 v66, 8, v66
	v_mov_b32_e32 v67, v1
	v_lshl_add_u64 v[70:71], v[70:71], 0, v[66:67]
	s_mov_b64 s[22:23], 0x4400d00
	s_mov_b32 s5, 0x4400000
	v_lshl_add_u64 v[86:87], v[70:71], 0, s[22:23]
	v_add_co_u32_e32 v70, vcc, s5, v70
	v_rcp_f32_e32 v74, v74
	s_nop 0
	v_addc_co_u32_e32 v71, vcc, 0, v71, vcc
	global_load_dwordx2 v[88:89], v[70:71], off offset:3328
	global_load_dwordx2 v[90:91], v[86:87], off offset:16
	global_load_dwordx2 v[82:83], v[86:87], off offset:32
	global_load_dwordx2 v[80:81], v[86:87], off offset:48
	global_load_dwordx2 v[78:79], v[86:87], off offset:64
	global_load_dwordx2 v[76:77], v[86:87], off offset:80
	global_load_dwordx2 v[72:73], v[86:87], off offset:96
	global_load_dwordx2 v[70:71], v[86:87], off offset:112
	v_pk_mul_f32 v[50:51], v[50:51], v[74:75] op_sel_hi:[1,0]
	s_movk_i32 s18, 0xf3c0
	v_mad_u64_u32 v[84:85], s[0:1], v75, s18, v[68:69]
	v_pk_mul_f32 v[52:53], v[52:53], v[74:75] op_sel_hi:[1,0]
	v_sub_u32_e32 v85, v85, v75
	v_lshl_add_u64 v[84:85], v[84:85], 0, v[0:1]
	v_pk_mul_f32 v[54:55], v[54:55], v[74:75] op_sel_hi:[1,0]
	v_pk_mul_f32 v[56:57], v[56:57], v[74:75] op_sel_hi:[1,0]
	v_pk_mul_f32 v[34:35], v[34:35], v[74:75] op_sel_hi:[1,0]
	v_pk_mul_f32 v[36:37], v[36:37], v[74:75] op_sel_hi:[1,0]
	v_pk_mul_f32 v[38:39], v[38:39], v[74:75] op_sel_hi:[1,0]
	v_pk_mul_f32 v[40:41], v[40:41], v[74:75] op_sel_hi:[1,0]
	s_mov_b64 s[0:1], 0x29800
	s_waitcnt vmcnt(7)
	v_lshlrev_b32_e32 v86, 16, v88
	v_and_b32_e32 v87, 0xffff0000, v88
	v_mul_f32_e32 v88, 0xbfb8aa3b, v86
	v_exp_f32_e32 v88, v88
	s_nop 0
	v_add_f32_e32 v88, 1.0, v88
	v_rcp_f32_e32 v92, v88
	v_mul_f32_e32 v88, 0xbfb8aa3b, v87
	v_exp_f32_e32 v88, v88
	s_nop 0
	v_add_f32_e32 v88, 1.0, v88
	v_rcp_f32_e32 v93, v88
	s_nop 0
	v_pk_mul_f32 v[86:87], v[92:93], v[86:87]
	s_nop 0
	v_pk_mul_f32 v[50:51], v[50:51], v[86:87]
	v_lshlrev_b32_e32 v86, 16, v89
	v_and_b32_e32 v87, 0xffff0000, v89
	v_mul_f32_e32 v88, 0xbfb8aa3b, v86
	v_mul_f32_e32 v89, 0xbfb8aa3b, v87
	v_exp_f32_e32 v88, v88
	v_exp_f32_e32 v89, v89
	v_add_f32_e32 v88, 1.0, v88
	v_add_f32_e32 v89, 1.0, v89
	v_rcp_f32_e32 v88, v88
	v_rcp_f32_e32 v89, v89
	s_nop 0
	v_pk_mul_f32 v[86:87], v[88:89], v[86:87]
	s_nop 0
	v_pk_mul_f32 v[52:53], v[52:53], v[86:87]
	v_cvt_pk_bf16_f32 v86, v50, v51
	v_cvt_pk_bf16_f32 v87, v52, v53
	s_waitcnt vmcnt(6)
	v_lshlrev_b32_e32 v52, 16, v90
	v_and_b32_e32 v53, 0xffff0000, v90
	v_lshl_add_u64 v[50:51], v[84:85], 0, v[66:67]
	v_mul_f32_e32 v84, 0xbfb8aa3b, v52
	v_mul_f32_e32 v85, 0xbfb8aa3b, v53
	v_exp_f32_e32 v84, v84
	v_exp_f32_e32 v85, v85
	v_mov_b32_e32 v106, v86
	v_mov_b32_e32 v107, v87
	v_add_f32_e32 v84, 1.0, v84
	v_add_f32_e32 v85, 1.0, v85
	v_rcp_f32_e32 v84, v84
	v_rcp_f32_e32 v85, v85
	s_nop 0
	v_pk_mul_f32 v[52:53], v[84:85], v[52:53]
	s_nop 0
	v_pk_mul_f32 v[52:53], v[54:55], v[52:53]
	v_lshlrev_b32_e32 v54, 16, v91
	v_and_b32_e32 v55, 0xffff0000, v91
	v_mul_f32_e32 v84, 0xbfb8aa3b, v54
	v_mul_f32_e32 v85, 0xbfb8aa3b, v55
	v_exp_f32_e32 v84, v84
	v_exp_f32_e32 v85, v85
	v_cvt_pk_bf16_f32 v52, v52, v53
	v_add_f32_e32 v84, 1.0, v84
	v_add_f32_e32 v85, 1.0, v85
	v_rcp_f32_e32 v84, v84
	v_rcp_f32_e32 v85, v85
	s_nop 0
	v_pk_mul_f32 v[54:55], v[84:85], v[54:55]
	s_nop 0
	v_pk_mul_f32 v[54:55], v[56:57], v[54:55]
	v_pk_mul_f32 v[56:57], v[58:59], v[74:75] op_sel_hi:[1,0]
	v_cvt_pk_bf16_f32 v53, v54, v55
	v_lshl_add_u64 v[110:111], v[50:51], 0, v[108:109]
	v_mov_b32_e32 v104, v52
	v_mov_b32_e32 v105, v53
	s_nop 1
	v_permlane32_swap_b32_e32 v104, v106
	v_permlane32_swap_b32_e32 v105, v107
	global_store_dwordx4 v[110:111], v[104:107], off offset:768
	s_waitcnt vmcnt(6)
	v_lshlrev_b32_e32 v52, 16, v82
	v_and_b32_e32 v53, 0xffff0000, v82
	v_mul_f32_e32 v54, 0xbfb8aa3b, v52
	v_mul_f32_e32 v55, 0xbfb8aa3b, v53
	v_exp_f32_e32 v54, v54
	v_exp_f32_e32 v55, v55
	v_pk_mul_f32 v[58:59], v[60:61], v[74:75] op_sel_hi:[1,0]
	v_add_f32_e32 v54, 1.0, v54
	v_add_f32_e32 v55, 1.0, v55
	v_rcp_f32_e32 v54, v54
	v_rcp_f32_e32 v55, v55
	s_nop 0
	v_pk_mul_f32 v[52:53], v[54:55], v[52:53]
	v_lshlrev_b32_e32 v54, 16, v83
	v_and_b32_e32 v55, 0xffff0000, v83
	v_pk_mul_f32 v[52:53], v[56:57], v[52:53]
	v_mul_f32_e32 v56, 0xbfb8aa3b, v54
	v_mul_f32_e32 v57, 0xbfb8aa3b, v55
	v_exp_f32_e32 v56, v56
	v_exp_f32_e32 v57, v57
	v_cvt_pk_bf16_f32 v52, v52, v53
	v_add_f32_e32 v56, 1.0, v56
	v_add_f32_e32 v57, 1.0, v57
	v_rcp_f32_e32 v56, v56
	v_rcp_f32_e32 v57, v57
	s_nop 0
	v_pk_mul_f32 v[54:55], v[56:57], v[54:55]
	s_nop 0
	v_pk_mul_f32 v[54:55], v[58:59], v[54:55]
	v_pk_mul_f32 v[56:57], v[62:63], v[74:75] op_sel_hi:[1,0]
	v_cvt_pk_bf16_f32 v53, v54, v55
	v_mov_b32_e32 v106, v52
	v_mov_b32_e32 v107, v53
	s_waitcnt vmcnt(5)
	v_lshlrev_b32_e32 v52, 16, v80
	v_and_b32_e32 v53, 0xffff0000, v80
	v_mul_f32_e32 v54, 0xbfb8aa3b, v52
	v_mul_f32_e32 v55, 0xbfb8aa3b, v53
	v_exp_f32_e32 v54, v54
	v_exp_f32_e32 v55, v55
	v_pk_mul_f32 v[58:59], v[64:65], v[74:75] op_sel_hi:[1,0]
	v_add_f32_e32 v54, 1.0, v54
	v_add_f32_e32 v55, 1.0, v55
	v_rcp_f32_e32 v54, v54
	v_rcp_f32_e32 v55, v55
	s_nop 0
	v_pk_mul_f32 v[52:53], v[54:55], v[52:53]
	v_lshlrev_b32_e32 v54, 16, v81
	v_and_b32_e32 v55, 0xffff0000, v81
	v_pk_mul_f32 v[52:53], v[56:57], v[52:53]
	v_mul_f32_e32 v56, 0xbfb8aa3b, v54
	v_mul_f32_e32 v57, 0xbfb8aa3b, v55
	v_exp_f32_e32 v56, v56
	v_exp_f32_e32 v57, v57
	v_cvt_pk_bf16_f32 v52, v52, v53
	v_add_f32_e32 v56, 1.0, v56
	v_add_f32_e32 v57, 1.0, v57
	v_rcp_f32_e32 v56, v56
	v_rcp_f32_e32 v57, v57
	s_nop 0
	v_pk_mul_f32 v[54:55], v[56:57], v[54:55]
	s_nop 0
	v_pk_mul_f32 v[54:55], v[58:59], v[54:55]
	s_nop 0
	v_cvt_pk_bf16_f32 v53, v54, v55
	v_mov_b32_e32 v104, v52
	v_mov_b32_e32 v105, v53
	s_nop 1
	v_permlane32_swap_b32_e32 v104, v106
	v_permlane32_swap_b32_e32 v105, v107
	global_store_dwordx4 v[110:111], v[104:107], off offset:800
	s_waitcnt vmcnt(5)
	v_lshlrev_b32_e32 v52, 16, v78
	v_and_b32_e32 v53, 0xffff0000, v78
	v_mul_f32_e32 v54, 0xbfb8aa3b, v52
	v_mul_f32_e32 v55, 0xbfb8aa3b, v53
	v_exp_f32_e32 v54, v54
	v_exp_f32_e32 v55, v55
	v_add_f32_e32 v54, 1.0, v54
	v_add_f32_e32 v55, 1.0, v55
	v_rcp_f32_e32 v54, v54
	v_rcp_f32_e32 v55, v55
	s_nop 0
	v_pk_mul_f32 v[52:53], v[54:55], v[52:53]
	s_nop 0
	v_pk_mul_f32 v[34:35], v[34:35], v[52:53]
	v_lshlrev_b32_e32 v52, 16, v79
	v_and_b32_e32 v53, 0xffff0000, v79
	v_mul_f32_e32 v54, 0xbfb8aa3b, v52
	v_mul_f32_e32 v55, 0xbfb8aa3b, v53
	v_exp_f32_e32 v54, v54
	v_exp_f32_e32 v55, v55
	v_cvt_pk_bf16_f32 v34, v34, v35
	v_add_f32_e32 v54, 1.0, v54
	v_add_f32_e32 v55, 1.0, v55
	v_rcp_f32_e32 v54, v54
	v_rcp_f32_e32 v55, v55
	s_nop 0
	v_pk_mul_f32 v[52:53], v[54:55], v[52:53]
	s_nop 0
	v_pk_mul_f32 v[36:37], v[36:37], v[52:53]
	s_nop 0
	v_cvt_pk_bf16_f32 v35, v36, v37
	v_mov_b32_e32 v106, v34
	v_mov_b32_e32 v107, v35
	s_waitcnt vmcnt(4)
	v_lshlrev_b32_e32 v34, 16, v76
	v_and_b32_e32 v35, 0xffff0000, v76
	v_mul_f32_e32 v36, 0xbfb8aa3b, v34
	v_mul_f32_e32 v37, 0xbfb8aa3b, v35
	v_exp_f32_e32 v36, v36
	v_exp_f32_e32 v37, v37
	v_add_f32_e32 v36, 1.0, v36
	v_add_f32_e32 v37, 1.0, v37
	v_rcp_f32_e32 v36, v36
	v_rcp_f32_e32 v37, v37
	s_nop 0
	v_pk_mul_f32 v[34:35], v[36:37], v[34:35]
	v_lshlrev_b32_e32 v36, 16, v77
	v_and_b32_e32 v37, 0xffff0000, v77
	v_pk_mul_f32 v[34:35], v[38:39], v[34:35]
	v_mul_f32_e32 v38, 0xbfb8aa3b, v36
	v_mul_f32_e32 v39, 0xbfb8aa3b, v37
	v_exp_f32_e32 v38, v38
	v_exp_f32_e32 v39, v39
	v_cvt_pk_bf16_f32 v34, v34, v35
	v_add_f32_e32 v38, 1.0, v38
	v_add_f32_e32 v39, 1.0, v39
	v_rcp_f32_e32 v38, v38
	v_rcp_f32_e32 v39, v39
	s_nop 0
	v_pk_mul_f32 v[36:37], v[38:39], v[36:37]
	s_nop 0
	v_pk_mul_f32 v[36:37], v[40:41], v[36:37]
	v_pk_mul_f32 v[38:39], v[42:43], v[74:75] op_sel_hi:[1,0]
	v_cvt_pk_bf16_f32 v35, v36, v37
	v_mov_b32_e32 v104, v34
	v_mov_b32_e32 v105, v35
	s_nop 1
	v_permlane32_swap_b32_e32 v104, v106
	v_permlane32_swap_b32_e32 v105, v107
	global_store_dwordx4 v[110:111], v[104:107], off offset:832
	s_waitcnt vmcnt(4)
	v_lshlrev_b32_e32 v34, 16, v72
	v_and_b32_e32 v35, 0xffff0000, v72
	v_mul_f32_e32 v36, 0xbfb8aa3b, v34
	v_mul_f32_e32 v37, 0xbfb8aa3b, v35
	v_exp_f32_e32 v36, v36
	v_exp_f32_e32 v37, v37
	v_pk_mul_f32 v[40:41], v[44:45], v[74:75] op_sel_hi:[1,0]
	v_add_f32_e32 v36, 1.0, v36
	v_add_f32_e32 v37, 1.0, v37
	v_rcp_f32_e32 v36, v36
	v_rcp_f32_e32 v37, v37
	s_nop 0
	v_pk_mul_f32 v[34:35], v[36:37], v[34:35]
	v_lshlrev_b32_e32 v36, 16, v73
	v_and_b32_e32 v37, 0xffff0000, v73
	v_pk_mul_f32 v[34:35], v[38:39], v[34:35]
	v_mul_f32_e32 v38, 0xbfb8aa3b, v36
	v_mul_f32_e32 v39, 0xbfb8aa3b, v37
	v_exp_f32_e32 v38, v38
	v_exp_f32_e32 v39, v39
	v_cvt_pk_bf16_f32 v34, v34, v35
	v_add_f32_e32 v38, 1.0, v38
	v_add_f32_e32 v39, 1.0, v39
	v_rcp_f32_e32 v38, v38
	v_rcp_f32_e32 v39, v39
	s_nop 0
	v_pk_mul_f32 v[36:37], v[38:39], v[36:37]
	s_nop 0
	v_pk_mul_f32 v[36:37], v[40:41], v[36:37]
	v_pk_mul_f32 v[38:39], v[46:47], v[74:75] op_sel_hi:[1,0]
	v_cvt_pk_bf16_f32 v35, v36, v37
	v_mov_b32_e32 v106, v34
	v_mov_b32_e32 v107, v35
	s_waitcnt vmcnt(3)
	v_lshlrev_b32_e32 v34, 16, v70
	v_and_b32_e32 v35, 0xffff0000, v70
	v_mul_f32_e32 v36, 0xbfb8aa3b, v34
	v_mul_f32_e32 v37, 0xbfb8aa3b, v35
	v_exp_f32_e32 v36, v36
	v_exp_f32_e32 v37, v37
	v_pk_mul_f32 v[40:41], v[48:49], v[74:75] op_sel_hi:[1,0]
	v_add_f32_e32 v36, 1.0, v36
	v_add_f32_e32 v37, 1.0, v37
	v_rcp_f32_e32 v36, v36
	v_rcp_f32_e32 v37, v37
	s_nop 0
	v_pk_mul_f32 v[34:35], v[36:37], v[34:35]
	v_lshlrev_b32_e32 v36, 16, v71
	v_and_b32_e32 v37, 0xffff0000, v71
	v_pk_mul_f32 v[34:35], v[38:39], v[34:35]
	v_mul_f32_e32 v38, 0xbfb8aa3b, v36
	v_mul_f32_e32 v39, 0xbfb8aa3b, v37
	v_exp_f32_e32 v38, v38
	v_exp_f32_e32 v39, v39
	v_cvt_pk_bf16_f32 v34, v34, v35
	v_add_f32_e32 v38, 1.0, v38
	v_add_f32_e32 v39, 1.0, v39
	v_rcp_f32_e32 v38, v38
	v_rcp_f32_e32 v39, v39
	s_nop 0
	v_pk_mul_f32 v[36:37], v[38:39], v[36:37]
	s_nop 0
	v_pk_mul_f32 v[36:37], v[40:41], v[36:37]
	v_or_b32_e32 v38, 32, v75
	v_cvt_pk_bf16_f32 v35, v36, v37
	v_mov_b32_e32 v104, v34
	v_mov_b32_e32 v105, v35
	s_nop 1
	v_permlane32_swap_b32_e32 v104, v106
	v_permlane32_swap_b32_e32 v105, v107
	global_store_dwordx4 v[110:111], v[104:107], off offset:864
	v_mov_b32_e32 v34, v150
	s_nop 1
	v_permlane32_swap_b32_e32 v150, v34
	v_add_f32_e32 v54, v150, v34
	v_lshl_add_u64 v[34:35], v[68:69], 0, s[0:1]
	v_lshl_add_u64 v[36:37], v[34:35], 0, v[0:1]
	v_lshl_add_u64 v[36:37], v[36:37], 0, v[66:67]
	v_mad_u64_u32 v[52:53], s[0:1], v38, s18, v[34:35]
	v_lshl_add_u64 v[34:35], v[36:37], 0, s[22:23]
	v_add_co_u32_e32 v36, vcc, s5, v36
	v_sub_u32_e32 v53, v53, v38
	s_nop 0
	v_addc_co_u32_e32 v37, vcc, 0, v37, vcc
	global_load_dwordx2 v[50:51], v[36:37], off offset:3328
	global_load_dwordx2 v[48:49], v[34:35], off offset:16
	global_load_dwordx2 v[46:47], v[34:35], off offset:32
	global_load_dwordx2 v[44:45], v[34:35], off offset:48
	global_load_dwordx2 v[42:43], v[34:35], off offset:64
	global_load_dwordx2 v[40:41], v[34:35], off offset:80
	global_load_dwordx2 v[38:39], v[34:35], off offset:96
	global_load_dwordx2 v[36:37], v[34:35], off offset:112
	v_rcp_f32_e32 v34, v54
	v_lshl_add_u64 v[52:53], v[52:53], 0, v[0:1]
	s_mov_b64 s[0:1], 0
	v_pk_mul_f32 v[18:19], v[18:19], v[34:35] op_sel_hi:[1,0]
	v_pk_mul_f32 v[20:21], v[20:21], v[34:35] op_sel_hi:[1,0]
	v_pk_mul_f32 v[22:23], v[22:23], v[34:35] op_sel_hi:[1,0]
	v_pk_mul_f32 v[24:25], v[24:25], v[34:35] op_sel_hi:[1,0]
	v_pk_mul_f32 v[2:3], v[2:3], v[34:35] op_sel_hi:[1,0]
	v_pk_mul_f32 v[4:5], v[4:5], v[34:35] op_sel_hi:[1,0]
	v_pk_mul_f32 v[6:7], v[6:7], v[34:35] op_sel_hi:[1,0]
	v_pk_mul_f32 v[8:9], v[8:9], v[34:35] op_sel_hi:[1,0]
	s_waitcnt vmcnt(7)
	v_lshlrev_b32_e32 v54, 16, v50
	v_mul_f32_e32 v0, 0xbfb8aa3b, v54
	v_exp_f32_e32 v0, v0
	v_and_b32_e32 v55, 0xffff0000, v50
	v_lshlrev_b32_e32 v50, 16, v51
	v_and_b32_e32 v51, 0xffff0000, v51
	v_add_f32_e32 v0, 1.0, v0
	v_rcp_f32_e32 v56, v0
	v_mul_f32_e32 v0, 0xbfb8aa3b, v55
	v_exp_f32_e32 v0, v0
	s_nop 0
	v_add_f32_e32 v0, 1.0, v0
	v_rcp_f32_e32 v57, v0
	v_mul_f32_e32 v0, 0xbfb8aa3b, v50
	v_exp_f32_e32 v0, v0
	v_pk_mul_f32 v[54:55], v[56:57], v[54:55]
	s_nop 0
	v_pk_mul_f32 v[18:19], v[18:19], v[54:55]
	v_add_f32_e32 v0, 1.0, v0
	v_rcp_f32_e32 v54, v0
	v_mul_f32_e32 v0, 0xbfb8aa3b, v51
	v_exp_f32_e32 v0, v0
	s_nop 0
	v_add_f32_e32 v0, 1.0, v0
	v_rcp_f32_e32 v55, v0
	s_nop 0
	v_pk_mul_f32 v[50:51], v[54:55], v[50:51]
	s_nop 0
	v_pk_mul_f32 v[20:21], v[20:21], v[50:51]
	v_cvt_pk_bf16_f32 v50, v18, v19
	v_cvt_pk_bf16_f32 v51, v20, v21
	s_waitcnt vmcnt(6)
	v_lshlrev_b32_e32 v20, 16, v48
	v_mul_f32_e32 v0, 0xbfb8aa3b, v20
	v_exp_f32_e32 v0, v0
	v_lshl_add_u64 v[18:19], v[52:53], 0, v[66:67]
	v_and_b32_e32 v21, 0xffff0000, v48
	v_mov_b32_e32 v106, v50
	v_mov_b32_e32 v107, v51
	v_add_f32_e32 v0, 1.0, v0
	v_rcp_f32_e32 v50, v0
	v_mul_f32_e32 v0, 0xbfb8aa3b, v21
	v_exp_f32_e32 v0, v0
	s_nop 0
	v_add_f32_e32 v0, 1.0, v0
	v_rcp_f32_e32 v51, v0
	s_nop 0
	v_pk_mul_f32 v[20:21], v[50:51], v[20:21]
	s_nop 0
	v_pk_mul_f32 v[20:21], v[22:23], v[20:21]
	v_lshlrev_b32_e32 v22, 16, v49
	v_mul_f32_e32 v0, 0xbfb8aa3b, v22
	v_exp_f32_e32 v0, v0
	v_and_b32_e32 v23, 0xffff0000, v49
	v_cvt_pk_bf16_f32 v20, v20, v21
	v_add_f32_e32 v0, 1.0, v0
	v_rcp_f32_e32 v48, v0
	v_mul_f32_e32 v0, 0xbfb8aa3b, v23
	v_exp_f32_e32 v0, v0
	s_nop 0
	v_add_f32_e32 v0, 1.0, v0
	v_rcp_f32_e32 v49, v0
	s_nop 0
	v_pk_mul_f32 v[22:23], v[48:49], v[22:23]
	s_nop 0
	v_pk_mul_f32 v[22:23], v[24:25], v[22:23]
	v_pk_mul_f32 v[24:25], v[26:27], v[34:35] op_sel_hi:[1,0]
	v_cvt_pk_bf16_f32 v21, v22, v23
	v_lshl_add_u64 v[112:113], v[18:19], 0, v[108:109]
	v_mov_b32_e32 v104, v20
	v_mov_b32_e32 v105, v21
	s_nop 1
	v_permlane32_swap_b32_e32 v104, v106
	v_permlane32_swap_b32_e32 v105, v107
	global_store_dwordx4 v[112:113], v[104:107], off offset:768
	s_waitcnt vmcnt(6)
	v_lshlrev_b32_e32 v20, 16, v46
	v_mul_f32_e32 v0, 0xbfb8aa3b, v20
	v_exp_f32_e32 v0, v0
	v_and_b32_e32 v21, 0xffff0000, v46
	v_pk_mul_f32 v[26:27], v[28:29], v[34:35] op_sel_hi:[1,0]
	v_add_f32_e32 v0, 1.0, v0
	v_rcp_f32_e32 v22, v0
	v_mul_f32_e32 v0, 0xbfb8aa3b, v21
	v_exp_f32_e32 v0, v0
	s_nop 0
	v_add_f32_e32 v0, 1.0, v0
	v_rcp_f32_e32 v23, v0
	s_nop 0
	v_pk_mul_f32 v[20:21], v[22:23], v[20:21]
	v_lshlrev_b32_e32 v22, 16, v47
	v_mul_f32_e32 v0, 0xbfb8aa3b, v22
	v_exp_f32_e32 v0, v0
	v_and_b32_e32 v23, 0xffff0000, v47
	v_pk_mul_f32 v[20:21], v[24:25], v[20:21]
	v_add_f32_e32 v0, 1.0, v0
	v_rcp_f32_e32 v24, v0
	v_mul_f32_e32 v0, 0xbfb8aa3b, v23
	v_exp_f32_e32 v0, v0
	v_cvt_pk_bf16_f32 v20, v20, v21
	v_add_f32_e32 v0, 1.0, v0
	v_rcp_f32_e32 v25, v0
	s_nop 0
	v_pk_mul_f32 v[22:23], v[24:25], v[22:23]
	s_nop 0
	v_pk_mul_f32 v[22:23], v[26:27], v[22:23]
	v_pk_mul_f32 v[24:25], v[30:31], v[34:35] op_sel_hi:[1,0]
	v_cvt_pk_bf16_f32 v21, v22, v23
	v_mov_b32_e32 v106, v20
	v_mov_b32_e32 v107, v21
	s_waitcnt vmcnt(5)
	v_lshlrev_b32_e32 v20, 16, v44
	v_mul_f32_e32 v0, 0xbfb8aa3b, v20
	v_exp_f32_e32 v0, v0
	v_and_b32_e32 v21, 0xffff0000, v44
	v_pk_mul_f32 v[26:27], v[32:33], v[34:35] op_sel_hi:[1,0]
	v_add_f32_e32 v0, 1.0, v0
	v_rcp_f32_e32 v22, v0
	v_mul_f32_e32 v0, 0xbfb8aa3b, v21
	v_exp_f32_e32 v0, v0
	s_nop 0
	v_add_f32_e32 v0, 1.0, v0
	v_rcp_f32_e32 v23, v0
	s_nop 0
	v_pk_mul_f32 v[20:21], v[22:23], v[20:21]
	v_lshlrev_b32_e32 v22, 16, v45
	v_mul_f32_e32 v0, 0xbfb8aa3b, v22
	v_exp_f32_e32 v0, v0
	v_and_b32_e32 v23, 0xffff0000, v45
	v_pk_mul_f32 v[20:21], v[24:25], v[20:21]
	v_add_f32_e32 v0, 1.0, v0
	v_rcp_f32_e32 v24, v0
	v_mul_f32_e32 v0, 0xbfb8aa3b, v23
	v_exp_f32_e32 v0, v0
	v_cvt_pk_bf16_f32 v20, v20, v21
	v_add_f32_e32 v0, 1.0, v0
	v_rcp_f32_e32 v25, v0
	s_nop 0
	v_pk_mul_f32 v[22:23], v[24:25], v[22:23]
	s_nop 0
	v_pk_mul_f32 v[22:23], v[26:27], v[22:23]
	s_nop 0
	v_cvt_pk_bf16_f32 v21, v22, v23
	v_mov_b32_e32 v104, v20
	v_mov_b32_e32 v105, v21
	s_nop 1
	v_permlane32_swap_b32_e32 v104, v106
	v_permlane32_swap_b32_e32 v105, v107
	global_store_dwordx4 v[112:113], v[104:107], off offset:800
	s_waitcnt vmcnt(5)
	v_lshlrev_b32_e32 v20, 16, v42
	v_mul_f32_e32 v0, 0xbfb8aa3b, v20
	v_exp_f32_e32 v0, v0
	v_and_b32_e32 v21, 0xffff0000, v42
	v_add_f32_e32 v0, 1.0, v0
	v_rcp_f32_e32 v22, v0
	v_mul_f32_e32 v0, 0xbfb8aa3b, v21
	v_exp_f32_e32 v0, v0
	s_nop 0
	v_add_f32_e32 v0, 1.0, v0
	v_rcp_f32_e32 v23, v0
	s_nop 0
	v_pk_mul_f32 v[20:21], v[22:23], v[20:21]
	s_nop 0
	v_pk_mul_f32 v[2:3], v[2:3], v[20:21]
	v_lshlrev_b32_e32 v20, 16, v43
	v_mul_f32_e32 v0, 0xbfb8aa3b, v20
	v_exp_f32_e32 v0, v0
	v_and_b32_e32 v21, 0xffff0000, v43
	v_cvt_pk_bf16_f32 v2, v2, v3
	v_add_f32_e32 v0, 1.0, v0
	v_rcp_f32_e32 v22, v0
	v_mul_f32_e32 v0, 0xbfb8aa3b, v21
	v_exp_f32_e32 v0, v0
	s_nop 0
	v_add_f32_e32 v0, 1.0, v0
	v_rcp_f32_e32 v23, v0
	s_nop 0
	v_pk_mul_f32 v[20:21], v[22:23], v[20:21]
	s_nop 0
	v_pk_mul_f32 v[4:5], v[4:5], v[20:21]
	s_nop 0
	v_cvt_pk_bf16_f32 v3, v4, v5
	v_mov_b32_e32 v106, v2
	v_mov_b32_e32 v107, v3
	s_waitcnt vmcnt(4)
	v_lshlrev_b32_e32 v2, 16, v40
	v_mul_f32_e32 v0, 0xbfb8aa3b, v2
	v_exp_f32_e32 v0, v0
	v_and_b32_e32 v3, 0xffff0000, v40
	v_add_f32_e32 v0, 1.0, v0
	v_rcp_f32_e32 v4, v0
	v_mul_f32_e32 v0, 0xbfb8aa3b, v3
	v_exp_f32_e32 v0, v0
	s_nop 0
	v_add_f32_e32 v0, 1.0, v0
	v_rcp_f32_e32 v5, v0
	s_nop 0
	v_pk_mul_f32 v[2:3], v[4:5], v[2:3]
	v_lshlrev_b32_e32 v4, 16, v41
	v_mul_f32_e32 v0, 0xbfb8aa3b, v4
	v_exp_f32_e32 v0, v0
	v_and_b32_e32 v5, 0xffff0000, v41
	v_pk_mul_f32 v[2:3], v[6:7], v[2:3]
	v_add_f32_e32 v0, 1.0, v0
	v_rcp_f32_e32 v6, v0
	v_mul_f32_e32 v0, 0xbfb8aa3b, v5
	v_exp_f32_e32 v0, v0
	v_cvt_pk_bf16_f32 v2, v2, v3
	v_add_f32_e32 v0, 1.0, v0
	v_rcp_f32_e32 v7, v0
	s_nop 0
	v_pk_mul_f32 v[4:5], v[6:7], v[4:5]
	s_nop 0
	v_pk_mul_f32 v[4:5], v[8:9], v[4:5]
	v_pk_mul_f32 v[6:7], v[10:11], v[34:35] op_sel_hi:[1,0]
	v_cvt_pk_bf16_f32 v3, v4, v5
	v_mov_b32_e32 v104, v2
	v_mov_b32_e32 v105, v3
	s_nop 1
	v_permlane32_swap_b32_e32 v104, v106
	v_permlane32_swap_b32_e32 v105, v107
	global_store_dwordx4 v[112:113], v[104:107], off offset:832
	s_waitcnt vmcnt(4)
	v_lshlrev_b32_e32 v2, 16, v38
	v_mul_f32_e32 v0, 0xbfb8aa3b, v2
	v_exp_f32_e32 v0, v0
	v_and_b32_e32 v3, 0xffff0000, v38
	v_pk_mul_f32 v[8:9], v[12:13], v[34:35] op_sel_hi:[1,0]
	v_add_f32_e32 v0, 1.0, v0
	v_rcp_f32_e32 v4, v0
	v_mul_f32_e32 v0, 0xbfb8aa3b, v3
	v_exp_f32_e32 v0, v0
	s_nop 0
	v_add_f32_e32 v0, 1.0, v0
	v_rcp_f32_e32 v5, v0
	s_nop 0
	v_pk_mul_f32 v[2:3], v[4:5], v[2:3]
	v_lshlrev_b32_e32 v4, 16, v39
	v_mul_f32_e32 v0, 0xbfb8aa3b, v4
	v_exp_f32_e32 v0, v0
	v_and_b32_e32 v5, 0xffff0000, v39
	v_pk_mul_f32 v[2:3], v[6:7], v[2:3]
	v_add_f32_e32 v0, 1.0, v0
	v_rcp_f32_e32 v6, v0
	v_mul_f32_e32 v0, 0xbfb8aa3b, v5
	v_exp_f32_e32 v0, v0
	v_cvt_pk_bf16_f32 v2, v2, v3
	v_add_f32_e32 v0, 1.0, v0
	v_rcp_f32_e32 v7, v0
	s_nop 0
	v_pk_mul_f32 v[4:5], v[6:7], v[4:5]
	s_nop 0
	v_pk_mul_f32 v[4:5], v[8:9], v[4:5]
	v_pk_mul_f32 v[6:7], v[14:15], v[34:35] op_sel_hi:[1,0]
	v_cvt_pk_bf16_f32 v3, v4, v5
	v_mov_b32_e32 v106, v2
	v_mov_b32_e32 v107, v3
	s_waitcnt vmcnt(3)
	v_lshlrev_b32_e32 v2, 16, v36
	v_mul_f32_e32 v0, 0xbfb8aa3b, v2
	v_exp_f32_e32 v0, v0
	v_and_b32_e32 v3, 0xffff0000, v36
	v_pk_mul_f32 v[8:9], v[16:17], v[34:35] op_sel_hi:[1,0]
	v_add_f32_e32 v0, 1.0, v0
	v_rcp_f32_e32 v4, v0
	v_mul_f32_e32 v0, 0xbfb8aa3b, v3
	v_exp_f32_e32 v0, v0
	s_nop 0
	v_add_f32_e32 v0, 1.0, v0
	v_rcp_f32_e32 v5, v0
	s_nop 0
	v_pk_mul_f32 v[2:3], v[4:5], v[2:3]
	v_lshlrev_b32_e32 v4, 16, v37
	v_mul_f32_e32 v0, 0xbfb8aa3b, v4
	v_exp_f32_e32 v0, v0
	v_and_b32_e32 v5, 0xffff0000, v37
	v_pk_mul_f32 v[2:3], v[6:7], v[2:3]
	v_add_f32_e32 v0, 1.0, v0
	v_rcp_f32_e32 v6, v0
	v_mul_f32_e32 v0, 0xbfb8aa3b, v5
	v_exp_f32_e32 v0, v0
	v_cvt_pk_bf16_f32 v2, v2, v3
	v_add_f32_e32 v0, 1.0, v0
	v_rcp_f32_e32 v7, v0
	s_nop 0
	v_pk_mul_f32 v[4:5], v[6:7], v[4:5]
	s_nop 0
	v_pk_mul_f32 v[4:5], v[8:9], v[4:5]
	s_nop 0
	v_cvt_pk_bf16_f32 v3, v4, v5
	v_mov_b32_e32 v104, v2
	v_mov_b32_e32 v105, v3
	s_nop 1
	v_permlane32_swap_b32_e32 v104, v106
	v_permlane32_swap_b32_e32 v105, v107
	global_store_dwordx4 v[112:113], v[104:107], off offset:864

.LBB0_195:
	s_waitcnt vmcnt(0)
	s_barrier
	v_mbcnt_lo_u32_b32 v108, -1, 0
	v_mbcnt_hi_u32_b32 v108, -1, v108
	v_cmp_gt_u32_e32 vcc, 32, v108
	s_nop 1
	v_cndmask_b32_e64 v109, -1, 0, vcc
	v_cndmask_b32_e64 v108, -8, 16, vcc
	v_mbcnt_lo_u32_b32 v68, -1, 0
	v_mbcnt_hi_u32_b32 v68, -1, v68
	s_movk_i32 s0, 0x100
	v_add_u32_e32 v0, s77, v68
	v_mov_b32_e32 v66, s20
	v_mov_b32_e32 v67, s9
	v_cmp_gt_u32_e32 vcc, s0, v0
	v_mov_b32_e32 v69, s21
	v_and_b32_e32 v0, 0xc0, v0
	v_cndmask_b32_e32 v66, v66, v67, vcc
	v_mov_b32_e32 v67, s43
	v_cndmask_b32_e32 v67, v67, v69, vcc
	v_lshl_or_b32 v0, v67, 8, v0
	v_add_u32_e32 v0, s45, v0
	v_and_or_b32 v82, v68, 31, v0
	v_lshlrev_b32_e32 v0, 7, v66
	v_mov_b64_e32 v[66:67], s[74:75]
	v_mad_u64_u32 v[66:67], s[0:1], v82, s4, v[66:67]
	v_lshrrev_b32_e32 v68, 2, v68
	v_and_b32_e32 v70, 8, v68
	v_mov_b32_e32 v71, v1
	v_lshl_add_u64 v[66:67], v[66:67], 0, v[0:1]
	v_lshl_add_u64 v[68:69], v[66:67], 0, v[70:71]
	v_add_co_u32_e32 v66, vcc, s42, v68
	s_mov_b64 s[0:1], 0x4400600
	s_nop 0
	v_addc_co_u32_e32 v67, vcc, 0, v69, vcc
	global_load_dwordx2 v[74:75], v[66:67], off offset:1536
	v_lshl_add_u64 v[76:77], v[68:69], 0, s[0:1]
	global_load_dwordx2 v[78:79], v[76:77], off offset:16
	global_load_dwordx2 v[72:73], v[76:77], off offset:32
	v_mov_b32_e32 v66, v251
	s_nop 1
	v_permlane32_swap_b32_e32 v251, v66
	v_add_f32_e32 v66, v251, v66
	v_rcp_f32_e32 v66, v66
	v_lshl_add_u64 v[80:81], s[74:75], 0, v[0:1]
	v_mad_u64_u32 v[80:81], s[0:1], v82, s33, v[80:81]
	v_pk_mul_f32 v[82:83], v[50:51], v[66:67] op_sel_hi:[1,0]
	v_pk_mul_f32 v[84:85], v[52:53], v[66:67] op_sel_hi:[1,0]
	v_pk_mul_f32 v[86:87], v[54:55], v[66:67] op_sel_hi:[1,0]
	v_pk_mul_f32 v[88:89], v[56:57], v[66:67] op_sel_hi:[1,0]
	v_lshl_add_u64 v[50:51], v[80:81], 0, v[70:71]
	global_load_dwordx2 v[80:81], v[76:77], off offset:48
	global_load_dwordx2 v[70:71], v[76:77], off offset:64
	global_load_dwordx2 v[56:57], v[76:77], off offset:80
	global_load_dwordx2 v[54:55], v[76:77], off offset:96
	global_load_dwordx2 v[52:53], v[76:77], off offset:112
	s_mov_b32 s0, 0x4429000
	v_mov_b32_e32 v210, 0x358637bd
	v_mov_b32_e32 v211, 0x3e91f4c4
	v_mov_b32_e32 v212, 0x3c0881c4
	v_mov_b32_e32 v213, 0xbab64f3b
	v_xor_b32_e32 v217, 16, v221
	s_waitcnt vmcnt(7)
	v_lshlrev_b32_e32 v76, 16, v74
	v_and_b32_e32 v77, 0xffff0000, v74
	v_lshlrev_b32_e32 v74, 16, v75
	v_and_b32_e32 v75, 0xffff0000, v75
	s_waitcnt vmcnt(6)
	v_lshlrev_b32_e32 v90, 16, v78
	v_and_b32_e32 v91, 0xffff0000, v78
	v_lshlrev_b32_e32 v78, 16, v79
	v_and_b32_e32 v79, 0xffff0000, v79
	v_mul_f32_e32 v0, 0xbfb8aa3b, v76
	v_mul_f32_e32 v67, 0xbfb8aa3b, v77
	v_mul_f32_e32 v93, 0xbfb8aa3b, v74
	v_mul_f32_e32 v94, 0xbfb8aa3b, v75
	v_mul_f32_e32 v95, 0xbfb8aa3b, v90
	v_mul_f32_e32 v96, 0xbfb8aa3b, v91
	v_mul_f32_e32 v97, 0xbfb8aa3b, v78
	v_mul_f32_e32 v98, 0xbfb8aa3b, v79
	v_exp_f32_e32 v0, v0
	v_exp_f32_e32 v67, v67
	v_exp_f32_e32 v93, v93
	v_exp_f32_e32 v94, v94
	v_exp_f32_e32 v95, v95
	v_exp_f32_e32 v96, v96
	v_exp_f32_e32 v97, v97
	v_exp_f32_e32 v98, v98
	v_add_f32_e32 v0, 1.0, v0
	v_add_f32_e32 v67, 1.0, v67
	v_add_f32_e32 v93, 1.0, v93
	v_add_f32_e32 v99, 1.0, v94
	v_add_f32_e32 v100, 1.0, v95
	v_add_f32_e32 v101, 1.0, v96
	v_add_f32_e32 v102, 1.0, v97
	v_add_f32_e32 v103, 1.0, v98
	v_rcp_f32_e32 v94, v0
	v_rcp_f32_e32 v95, v67
	v_rcp_f32_e32 v96, v93
	v_rcp_f32_e32 v97, v99
	v_rcp_f32_e32 v98, v100
	v_rcp_f32_e32 v99, v101
	s_waitcnt vmcnt(5)
	v_lshlrev_b32_e32 v92, 16, v72
	v_rcp_f32_e32 v100, v102
	v_rcp_f32_e32 v101, v103
	v_mul_f32_e32 v0, 0xbfb8aa3b, v92
	v_and_b32_e32 v93, 0xffff0000, v72
	v_exp_f32_e32 v0, v0
	v_mul_f32_e32 v67, 0xbfb8aa3b, v93
	v_pk_mul_f32 v[76:77], v[94:95], v[76:77]
	v_pk_mul_f32 v[74:75], v[96:97], v[74:75]
	v_pk_mul_f32 v[90:91], v[98:99], v[90:91]
	v_exp_f32_e32 v67, v67
	v_pk_mul_f32 v[78:79], v[100:101], v[78:79]
	v_pk_mul_f32 v[76:77], v[82:83], v[76:77]
	v_pk_mul_f32 v[74:75], v[84:85], v[74:75]
	v_pk_mul_f32 v[82:83], v[86:87], v[90:91]
	v_pk_mul_f32 v[78:79], v[88:89], v[78:79]
	v_cvt_pk_bf16_f32 v76, v76, v77
	v_cvt_pk_bf16_f32 v77, v74, v75
	v_cvt_pk_bf16_f32 v74, v82, v83
	v_cvt_pk_bf16_f32 v75, v78, v79
	v_mov_b32_e32 v106, v76
	v_mov_b32_e32 v107, v77
	v_lshl_add_u64 v[110:111], v[50:51], 0, v[108:109]
	v_mov_b32_e32 v104, v74
	v_mov_b32_e32 v105, v75
	s_nop 1
	v_permlane32_swap_b32_e32 v104, v106
	v_permlane32_swap_b32_e32 v105, v107
	global_store_dwordx4 v[110:111], v[104:107], off
	v_add_f32_e32 v0, 1.0, v0
	v_lshlrev_b32_e32 v74, 16, v73
	v_rcp_f32_e32 v72, v0
	v_pk_mul_f32 v[58:59], v[58:59], v[66:67] op_sel_hi:[1,0]
	v_add_f32_e32 v0, 1.0, v67
	v_and_b32_e32 v75, 0xffff0000, v73
	v_mul_f32_e32 v67, 0xbfb8aa3b, v74
	v_exp_f32_e32 v67, v67
	v_mul_f32_e32 v73, 0xbfb8aa3b, v75
	v_exp_f32_e32 v77, v73
	v_rcp_f32_e32 v73, v0
	v_add_f32_e32 v0, 1.0, v67
	v_rcp_f32_e32 v76, v0
	v_add_f32_e32 v0, 1.0, v77
	v_rcp_f32_e32 v77, v0
	v_pk_mul_f32 v[72:73], v[72:73], v[92:93]
	v_pk_mul_f32 v[60:61], v[60:61], v[66:67] op_sel_hi:[1,0]
	v_pk_mul_f32 v[58:59], v[58:59], v[72:73]
	v_pk_mul_f32 v[72:73], v[76:77], v[74:75]
	v_cvt_pk_bf16_f32 v58, v58, v59
	v_pk_mul_f32 v[60:61], v[60:61], v[72:73]
	s_waitcnt vmcnt(5)
	v_lshlrev_b32_e32 v72, 16, v81
	v_cvt_pk_bf16_f32 v59, v60, v61
	v_mov_b32_e32 v106, v58
	v_mov_b32_e32 v107, v59
	v_lshlrev_b32_e32 v58, 16, v80
	v_mul_f32_e32 v0, 0xbfb8aa3b, v58
	v_and_b32_e32 v59, 0xffff0000, v80
	v_exp_f32_e32 v0, v0
	v_mul_f32_e32 v60, 0xbfb8aa3b, v59
	v_exp_f32_e32 v61, v60
	v_and_b32_e32 v73, 0xffff0000, v81
	v_add_f32_e32 v0, 1.0, v0
	v_rcp_f32_e32 v60, v0
	v_add_f32_e32 v0, 1.0, v61
	v_mul_f32_e32 v61, 0xbfb8aa3b, v72
	v_pk_mul_f32 v[62:63], v[62:63], v[66:67] op_sel_hi:[1,0]
	v_exp_f32_e32 v67, v61
	v_mul_f32_e32 v61, 0xbfb8aa3b, v73
	v_exp_f32_e32 v75, v61
	v_rcp_f32_e32 v61, v0
	v_add_f32_e32 v0, 1.0, v67
	v_rcp_f32_e32 v74, v0
	v_add_f32_e32 v0, 1.0, v75
	v_rcp_f32_e32 v75, v0
	v_pk_mul_f32 v[58:59], v[60:61], v[58:59]
	v_pk_mul_f32 v[60:61], v[64:65], v[66:67] op_sel_hi:[1,0]
	v_pk_mul_f32 v[58:59], v[62:63], v[58:59]
	v_pk_mul_f32 v[62:63], v[74:75], v[72:73]
	v_cvt_pk_bf16_f32 v58, v58, v59
	v_pk_mul_f32 v[60:61], v[60:61], v[62:63]
	s_waitcnt vmcnt(4)
	v_lshlrev_b32_e32 v62, 16, v71
	v_cvt_pk_bf16_f32 v59, v60, v61
	v_mov_b32_e32 v104, v58
	v_mov_b32_e32 v105, v59
	s_nop 1
	v_permlane32_swap_b32_e32 v104, v106
	v_permlane32_swap_b32_e32 v105, v107
	global_store_dwordx4 v[110:111], v[104:107], off offset:32
	v_lshlrev_b32_e32 v58, 16, v70
	v_mul_f32_e32 v0, 0xbfb8aa3b, v58
	v_and_b32_e32 v59, 0xffff0000, v70
	v_exp_f32_e32 v0, v0
	v_mul_f32_e32 v60, 0xbfb8aa3b, v59
	v_exp_f32_e32 v61, v60
	v_and_b32_e32 v63, 0xffff0000, v71
	v_add_f32_e32 v0, 1.0, v0
	v_rcp_f32_e32 v60, v0
	v_add_f32_e32 v0, 1.0, v61
	v_mul_f32_e32 v61, 0xbfb8aa3b, v62
	v_exp_f32_e32 v64, v61
	v_mul_f32_e32 v61, 0xbfb8aa3b, v63
	v_exp_f32_e32 v65, v61
	v_rcp_f32_e32 v61, v0
	v_add_f32_e32 v0, 1.0, v64
	v_rcp_f32_e32 v64, v0
	v_add_f32_e32 v0, 1.0, v65
	v_rcp_f32_e32 v65, v0
	v_pk_mul_f32 v[34:35], v[34:35], v[66:67] op_sel_hi:[1,0]
	v_pk_mul_f32 v[58:59], v[60:61], v[58:59]
	v_pk_mul_f32 v[36:37], v[36:37], v[66:67] op_sel_hi:[1,0]
	v_pk_mul_f32 v[34:35], v[34:35], v[58:59]
	v_pk_mul_f32 v[58:59], v[64:65], v[62:63]
	v_cvt_pk_bf16_f32 v34, v34, v35
	v_pk_mul_f32 v[36:37], v[36:37], v[58:59]
	v_pk_mul_f32 v[38:39], v[38:39], v[66:67] op_sel_hi:[1,0]
	v_cvt_pk_bf16_f32 v35, v36, v37
	v_mov_b32_e32 v106, v34
	v_mov_b32_e32 v107, v35
	s_waitcnt vmcnt(4)
	v_lshlrev_b32_e32 v34, 16, v56
	v_mul_f32_e32 v0, 0xbfb8aa3b, v34
	v_and_b32_e32 v35, 0xffff0000, v56
	v_exp_f32_e32 v0, v0
	v_mul_f32_e32 v36, 0xbfb8aa3b, v35
	v_exp_f32_e32 v37, v36
	v_lshlrev_b32_e32 v56, 16, v57
	v_add_f32_e32 v0, 1.0, v0
	v_rcp_f32_e32 v36, v0
	v_add_f32_e32 v0, 1.0, v37
	v_and_b32_e32 v57, 0xffff0000, v57
	v_mul_f32_e32 v37, 0xbfb8aa3b, v56
	v_exp_f32_e32 v58, v37
	v_mul_f32_e32 v37, 0xbfb8aa3b, v57
	v_exp_f32_e32 v59, v37
	v_rcp_f32_e32 v37, v0
	v_add_f32_e32 v0, 1.0, v58
	v_rcp_f32_e32 v58, v0
	v_add_f32_e32 v0, 1.0, v59
	v_rcp_f32_e32 v59, v0
	v_pk_mul_f32 v[34:35], v[36:37], v[34:35]
	v_pk_mul_f32 v[36:37], v[40:41], v[66:67] op_sel_hi:[1,0]
	v_pk_mul_f32 v[34:35], v[38:39], v[34:35]
	v_pk_mul_f32 v[38:39], v[58:59], v[56:57]
	v_add_co_u32_e32 v60, vcc, s0, v68
	v_pk_mul_f32 v[36:37], v[36:37], v[38:39]
	s_waitcnt vmcnt(3)
	v_lshlrev_b32_e32 v38, 16, v54
	v_and_b32_e32 v39, 0xffff0000, v54
	v_mul_f32_e32 v0, 0xbfb8aa3b, v38
	v_exp_f32_e32 v0, v0
	v_mul_f32_e32 v40, 0xbfb8aa3b, v39
	v_exp_f32_e32 v41, v40
	v_addc_co_u32_e32 v61, vcc, 0, v69, vcc
	global_load_dwordx2 v[60:61], v[60:61], off offset:3584
	v_add_f32_e32 v0, 1.0, v0
	v_rcp_f32_e32 v40, v0
	v_add_f32_e32 v0, 1.0, v41
	v_rcp_f32_e32 v41, v0
	v_cvt_pk_bf16_f32 v34, v34, v35
	v_cvt_pk_bf16_f32 v35, v36, v37
	v_mov_b32_e32 v104, v34
	v_mov_b32_e32 v105, v35
	s_nop 1
	v_permlane32_swap_b32_e32 v104, v106
	v_permlane32_swap_b32_e32 v105, v107
	global_store_dwordx4 v[110:111], v[104:107], off offset:64
	v_pk_mul_f32 v[36:37], v[40:41], v[38:39]
	v_lshlrev_b32_e32 v38, 16, v55
	v_and_b32_e32 v39, 0xffff0000, v55
	v_mul_f32_e32 v0, 0xbfb8aa3b, v38
	v_exp_f32_e32 v0, v0
	v_mul_f32_e32 v40, 0xbfb8aa3b, v39
	v_exp_f32_e32 v40, v40
	v_pk_mul_f32 v[34:35], v[42:43], v[66:67] op_sel_hi:[1,0]
	v_add_f32_e32 v0, 1.0, v0
	v_pk_mul_f32 v[34:35], v[34:35], v[36:37]
	v_rcp_f32_e32 v36, v0
	v_add_f32_e32 v0, 1.0, v40
	v_rcp_f32_e32 v37, v0
	s_mov_b64 s[0:1], 0x4429e00
	v_lshl_add_u64 v[42:43], v[68:69], 0, s[0:1]
	v_pk_mul_f32 v[40:41], v[44:45], v[66:67] op_sel_hi:[1,0]
	global_load_dwordx2 v[44:45], v[42:43], off offset:16
	v_pk_mul_f32 v[36:37], v[36:37], v[38:39]
	v_cvt_pk_bf16_f32 v34, v34, v35
	v_pk_mul_f32 v[36:37], v[40:41], v[36:37]
	s_waitcnt vmcnt(5)
	v_lshlrev_b32_e32 v40, 16, v53
	v_cvt_pk_bf16_f32 v35, v36, v37
	v_mov_b32_e32 v106, v34
	v_mov_b32_e32 v107, v35
	v_lshlrev_b32_e32 v34, 16, v52
	v_mul_f32_e32 v0, 0xbfb8aa3b, v34
	v_and_b32_e32 v35, 0xffff0000, v52
	v_exp_f32_e32 v0, v0
	v_mul_f32_e32 v36, 0xbfb8aa3b, v35
	v_exp_f32_e32 v37, v36
	v_and_b32_e32 v41, 0xffff0000, v53
	v_add_f32_e32 v0, 1.0, v0
	v_rcp_f32_e32 v36, v0
	v_add_f32_e32 v0, 1.0, v37
	v_rcp_f32_e32 v37, v0
	v_mul_f32_e32 v0, 0xbfb8aa3b, v40
	v_pk_mul_f32 v[38:39], v[46:47], v[66:67] op_sel_hi:[1,0]
	v_exp_f32_e32 v0, v0
	v_mul_f32_e32 v46, 0xbfb8aa3b, v41
	v_exp_f32_e32 v46, v46
	v_pk_mul_f32 v[34:35], v[36:37], v[34:35]
	v_add_f32_e32 v0, 1.0, v0
	v_rcp_f32_e32 v36, v0
	v_add_f32_e32 v0, 1.0, v46
	global_load_dwordx2 v[46:47], v[42:43], off offset:32
	v_rcp_f32_e32 v37, v0
	v_pk_mul_f32 v[34:35], v[38:39], v[34:35]
	v_pk_mul_f32 v[38:39], v[48:49], v[66:67] op_sel_hi:[1,0]
	v_cvt_pk_bf16_f32 v34, v34, v35
	v_pk_mul_f32 v[36:37], v[36:37], v[40:41]
	v_mov_b32_e32 v0, v250
	v_pk_mul_f32 v[36:37], v[38:39], v[36:37]
	s_nop 0
	v_permlane32_swap_b32_e32 v250, v0
	v_cvt_pk_bf16_f32 v35, v36, v37
	v_mov_b32_e32 v104, v34
	v_mov_b32_e32 v105, v35
	s_nop 1
	v_permlane32_swap_b32_e32 v104, v106
	v_permlane32_swap_b32_e32 v105, v107
	global_store_dwordx4 v[110:111], v[104:107], off offset:96
	global_load_dwordx2 v[40:41], v[42:43], off offset:48
	global_load_dwordx2 v[48:49], v[42:43], off offset:64
	global_load_dwordx2 v[38:39], v[42:43], off offset:80
	global_load_dwordx2 v[36:37], v[42:43], off offset:96
	s_nop 0
	global_load_dwordx2 v[34:35], v[42:43], off offset:112
	v_add_f32_e32 v0, v250, v0
	v_rcp_f32_e32 v0, v0
	s_mov_b64 s[0:1], 0x11000
	v_pk_mul_f32 v[18:19], v[18:19], v[0:1] op_sel_hi:[1,0]
	v_pk_mul_f32 v[20:21], v[20:21], v[0:1] op_sel_hi:[1,0]
	v_pk_mul_f32 v[22:23], v[22:23], v[0:1] op_sel_hi:[1,0]
	v_pk_mul_f32 v[2:3], v[2:3], v[0:1] op_sel_hi:[1,0]
	v_pk_mul_f32 v[4:5], v[4:5], v[0:1] op_sel_hi:[1,0]
	v_pk_mul_f32 v[6:7], v[6:7], v[0:1] op_sel_hi:[1,0]
	s_waitcnt vmcnt(9)
	v_lshlrev_b32_e32 v42, 16, v60
	v_mul_f32_e32 v43, 0xbfb8aa3b, v42
	v_exp_f32_e32 v52, v43
	v_and_b32_e32 v43, 0xffff0000, v60
	v_mul_f32_e32 v53, 0xbfb8aa3b, v43
	v_lshlrev_b32_e32 v54, 16, v61
	v_and_b32_e32 v55, 0xffff0000, v61
	v_exp_f32_e32 v53, v53
	v_mul_f32_e32 v56, 0xbfb8aa3b, v54
	v_mul_f32_e32 v57, 0xbfb8aa3b, v55
	v_exp_f32_e32 v56, v56
	v_exp_f32_e32 v57, v57
	v_add_f32_e32 v52, 1.0, v52
	v_add_f32_e32 v53, 1.0, v53
	v_rcp_f32_e32 v52, v52
	v_rcp_f32_e32 v53, v53
	v_add_f32_e32 v56, 1.0, v56
	v_add_f32_e32 v57, 1.0, v57
	v_rcp_f32_e32 v56, v56
	v_rcp_f32_e32 v57, v57
	v_pk_mul_f32 v[42:43], v[52:53], v[42:43]
	s_nop 0
	v_pk_mul_f32 v[18:19], v[18:19], v[42:43]
	v_pk_mul_f32 v[42:43], v[56:57], v[54:55]
	s_nop 0
	v_pk_mul_f32 v[20:21], v[20:21], v[42:43]
	v_cvt_pk_bf16_f32 v42, v18, v19
	v_lshl_add_u64 v[18:19], v[50:51], 0, s[0:1]
	s_mov_b32 s0, 0x11000
	v_cvt_pk_bf16_f32 v43, v20, v21
	v_add_co_u32_e32 v20, vcc, s0, v50
	s_nop 1
	v_addc_co_u32_e32 v21, vcc, 0, v51, vcc
	v_mov_b32_e32 v106, v42
	v_mov_b32_e32 v107, v43
	s_waitcnt vmcnt(7)
	v_lshlrev_b32_e32 v20, 16, v44
	v_mul_f32_e32 v21, 0xbfb8aa3b, v20
	v_exp_f32_e32 v42, v21
	v_and_b32_e32 v21, 0xffff0000, v44
	v_mul_f32_e32 v43, 0xbfb8aa3b, v21
	v_lshlrev_b32_e32 v44, 16, v45
	v_and_b32_e32 v45, 0xffff0000, v45
	v_exp_f32_e32 v43, v43
	v_mul_f32_e32 v50, 0xbfb8aa3b, v44
	v_mul_f32_e32 v51, 0xbfb8aa3b, v45
	v_exp_f32_e32 v50, v50
	v_exp_f32_e32 v51, v51
	v_add_f32_e32 v42, 1.0, v42
	v_add_f32_e32 v43, 1.0, v43
	v_rcp_f32_e32 v42, v42
	v_rcp_f32_e32 v43, v43
	v_add_f32_e32 v50, 1.0, v50
	v_add_f32_e32 v51, 1.0, v51
	v_rcp_f32_e32 v50, v50
	v_rcp_f32_e32 v51, v51
	v_pk_mul_f32 v[20:21], v[42:43], v[20:21]
	s_nop 0
	v_pk_mul_f32 v[20:21], v[22:23], v[20:21]
	v_pk_mul_f32 v[22:23], v[24:25], v[0:1] op_sel_hi:[1,0]
	v_pk_mul_f32 v[24:25], v[50:51], v[44:45]
	v_cvt_pk_bf16_f32 v20, v20, v21
	v_pk_mul_f32 v[22:23], v[22:23], v[24:25]
	v_pk_mul_f32 v[24:25], v[26:27], v[0:1] op_sel_hi:[1,0]
	v_cvt_pk_bf16_f32 v21, v22, v23
	v_lshl_add_u64 v[112:113], v[18:19], 0, v[108:109]
	v_mov_b32_e32 v104, v20
	v_mov_b32_e32 v105, v21
	s_nop 1
	v_permlane32_swap_b32_e32 v104, v106
	v_permlane32_swap_b32_e32 v105, v107
	global_store_dwordx4 v[112:113], v[104:107], off
	s_waitcnt vmcnt(7)
	v_lshlrev_b32_e32 v20, 16, v46
	v_mul_f32_e32 v21, 0xbfb8aa3b, v20
	v_exp_f32_e32 v22, v21
	v_and_b32_e32 v21, 0xffff0000, v46
	v_mul_f32_e32 v23, 0xbfb8aa3b, v21
	v_lshlrev_b32_e32 v26, 16, v47
	v_and_b32_e32 v27, 0xffff0000, v47
	v_exp_f32_e32 v23, v23
	v_mul_f32_e32 v42, 0xbfb8aa3b, v26
	v_mul_f32_e32 v43, 0xbfb8aa3b, v27
	v_exp_f32_e32 v42, v42
	v_exp_f32_e32 v43, v43
	v_add_f32_e32 v22, 1.0, v22
	v_add_f32_e32 v23, 1.0, v23
	v_rcp_f32_e32 v22, v22
	v_rcp_f32_e32 v23, v23
	v_add_f32_e32 v42, 1.0, v42
	v_add_f32_e32 v43, 1.0, v43
	v_rcp_f32_e32 v42, v42
	v_rcp_f32_e32 v43, v43
	v_pk_mul_f32 v[20:21], v[22:23], v[20:21]
	v_pk_mul_f32 v[22:23], v[28:29], v[0:1] op_sel_hi:[1,0]
	v_pk_mul_f32 v[20:21], v[24:25], v[20:21]
	v_pk_mul_f32 v[24:25], v[42:43], v[26:27]
	v_cvt_pk_bf16_f32 v20, v20, v21
	v_pk_mul_f32 v[22:23], v[22:23], v[24:25]
	s_waitcnt vmcnt(5)
	v_lshlrev_b32_e32 v26, 16, v41
	v_cvt_pk_bf16_f32 v21, v22, v23
	v_mov_b32_e32 v106, v20
	v_mov_b32_e32 v107, v21
	v_lshlrev_b32_e32 v20, 16, v40
	v_mul_f32_e32 v21, 0xbfb8aa3b, v20
	v_exp_f32_e32 v22, v21
	v_and_b32_e32 v21, 0xffff0000, v40
	v_mul_f32_e32 v23, 0xbfb8aa3b, v21
	v_and_b32_e32 v27, 0xffff0000, v41
	v_exp_f32_e32 v23, v23
	v_mul_f32_e32 v28, 0xbfb8aa3b, v26
	v_mul_f32_e32 v29, 0xbfb8aa3b, v27
	v_exp_f32_e32 v28, v28
	v_exp_f32_e32 v29, v29
	v_add_f32_e32 v22, 1.0, v22
	v_add_f32_e32 v23, 1.0, v23
	v_rcp_f32_e32 v22, v22
	v_rcp_f32_e32 v23, v23
	v_add_f32_e32 v28, 1.0, v28
	v_add_f32_e32 v29, 1.0, v29
	v_rcp_f32_e32 v28, v28
	v_rcp_f32_e32 v29, v29
	v_pk_mul_f32 v[24:25], v[30:31], v[0:1] op_sel_hi:[1,0]
	v_pk_mul_f32 v[20:21], v[22:23], v[20:21]
	v_pk_mul_f32 v[22:23], v[32:33], v[0:1] op_sel_hi:[1,0]
	v_pk_mul_f32 v[20:21], v[24:25], v[20:21]
	v_pk_mul_f32 v[24:25], v[28:29], v[26:27]
	v_cvt_pk_bf16_f32 v20, v20, v21
	v_pk_mul_f32 v[22:23], v[22:23], v[24:25]
	s_waitcnt vmcnt(4)
	v_lshlrev_b32_e32 v24, 16, v49
	v_cvt_pk_bf16_f32 v21, v22, v23
	v_mov_b32_e32 v104, v20
	v_mov_b32_e32 v105, v21
	s_nop 1
	v_permlane32_swap_b32_e32 v104, v106
	v_permlane32_swap_b32_e32 v105, v107
	global_store_dwordx4 v[112:113], v[104:107], off offset:32
	v_lshlrev_b32_e32 v20, 16, v48
	v_mul_f32_e32 v21, 0xbfb8aa3b, v20
	v_exp_f32_e32 v22, v21
	v_and_b32_e32 v21, 0xffff0000, v48
	v_mul_f32_e32 v23, 0xbfb8aa3b, v21
	v_and_b32_e32 v25, 0xffff0000, v49
	v_exp_f32_e32 v23, v23
	v_mul_f32_e32 v26, 0xbfb8aa3b, v24
	v_mul_f32_e32 v27, 0xbfb8aa3b, v25
	v_exp_f32_e32 v26, v26
	v_exp_f32_e32 v27, v27
	v_add_f32_e32 v22, 1.0, v22
	v_add_f32_e32 v23, 1.0, v23
	v_rcp_f32_e32 v22, v22
	v_rcp_f32_e32 v23, v23
	v_add_f32_e32 v26, 1.0, v26
	v_add_f32_e32 v27, 1.0, v27
	v_rcp_f32_e32 v26, v26
	v_rcp_f32_e32 v27, v27
	v_pk_mul_f32 v[20:21], v[22:23], v[20:21]
	s_nop 0
	v_pk_mul_f32 v[2:3], v[2:3], v[20:21]
	v_pk_mul_f32 v[20:21], v[26:27], v[24:25]
	v_cvt_pk_bf16_f32 v2, v2, v3
	v_pk_mul_f32 v[4:5], v[4:5], v[20:21]
	s_waitcnt vmcnt(4)
	v_lshlrev_b32_e32 v20, 16, v39
	v_cvt_pk_bf16_f32 v3, v4, v5
	v_mov_b32_e32 v106, v2
	v_mov_b32_e32 v107, v3
	v_lshlrev_b32_e32 v2, 16, v38
	v_mul_f32_e32 v3, 0xbfb8aa3b, v2
	v_exp_f32_e32 v4, v3
	v_and_b32_e32 v3, 0xffff0000, v38
	v_mul_f32_e32 v5, 0xbfb8aa3b, v3
	v_and_b32_e32 v21, 0xffff0000, v39
	v_exp_f32_e32 v5, v5
	v_mul_f32_e32 v22, 0xbfb8aa3b, v20
	v_mul_f32_e32 v23, 0xbfb8aa3b, v21
	v_exp_f32_e32 v22, v22
	v_exp_f32_e32 v23, v23
	v_add_f32_e32 v4, 1.0, v4
	v_add_f32_e32 v5, 1.0, v5
	v_rcp_f32_e32 v4, v4
	v_rcp_f32_e32 v5, v5
	v_add_f32_e32 v22, 1.0, v22
	v_add_f32_e32 v23, 1.0, v23
	v_rcp_f32_e32 v22, v22
	v_rcp_f32_e32 v23, v23
	v_pk_mul_f32 v[2:3], v[4:5], v[2:3]
	v_pk_mul_f32 v[4:5], v[8:9], v[0:1] op_sel_hi:[1,0]
	v_pk_mul_f32 v[2:3], v[6:7], v[2:3]
	v_pk_mul_f32 v[6:7], v[22:23], v[20:21]
	v_cvt_pk_bf16_f32 v2, v2, v3
	v_pk_mul_f32 v[4:5], v[4:5], v[6:7]
	s_waitcnt vmcnt(3)
	v_lshlrev_b32_e32 v8, 16, v37
	v_cvt_pk_bf16_f32 v3, v4, v5
	v_mov_b32_e32 v104, v2
	v_mov_b32_e32 v105, v3
	s_nop 1
	v_permlane32_swap_b32_e32 v104, v106
	v_permlane32_swap_b32_e32 v105, v107
	global_store_dwordx4 v[112:113], v[104:107], off offset:64
	v_lshlrev_b32_e32 v2, 16, v36
	v_mul_f32_e32 v3, 0xbfb8aa3b, v2
	v_exp_f32_e32 v4, v3
	v_and_b32_e32 v3, 0xffff0000, v36
	v_mul_f32_e32 v5, 0xbfb8aa3b, v3
	v_and_b32_e32 v9, 0xffff0000, v37
	v_exp_f32_e32 v5, v5
	v_pk_mul_f32 v[6:7], v[10:11], v[0:1] op_sel_hi:[1,0]
	v_mul_f32_e32 v10, 0xbfb8aa3b, v8
	v_mul_f32_e32 v11, 0xbfb8aa3b, v9
	v_exp_f32_e32 v10, v10
	v_exp_f32_e32 v11, v11
	v_add_f32_e32 v4, 1.0, v4
	v_add_f32_e32 v5, 1.0, v5
	v_rcp_f32_e32 v4, v4
	v_rcp_f32_e32 v5, v5
	v_add_f32_e32 v10, 1.0, v10
	v_add_f32_e32 v11, 1.0, v11
	v_rcp_f32_e32 v10, v10
	v_rcp_f32_e32 v11, v11
	v_pk_mul_f32 v[2:3], v[4:5], v[2:3]
	v_pk_mul_f32 v[4:5], v[12:13], v[0:1] op_sel_hi:[1,0]
	v_pk_mul_f32 v[2:3], v[6:7], v[2:3]
	v_pk_mul_f32 v[6:7], v[10:11], v[8:9]
	v_cvt_pk_bf16_f32 v2, v2, v3
	v_pk_mul_f32 v[4:5], v[4:5], v[6:7]
	s_waitcnt vmcnt(3)
	v_lshlrev_b32_e32 v8, 16, v35
	v_cvt_pk_bf16_f32 v3, v4, v5
	v_mov_b32_e32 v106, v2
	v_mov_b32_e32 v107, v3
	v_lshlrev_b32_e32 v2, 16, v34
	v_mul_f32_e32 v3, 0xbfb8aa3b, v2
	v_exp_f32_e32 v4, v3
	v_and_b32_e32 v3, 0xffff0000, v34
	v_mul_f32_e32 v5, 0xbfb8aa3b, v3
	v_and_b32_e32 v9, 0xffff0000, v35
	v_exp_f32_e32 v5, v5
	v_mul_f32_e32 v10, 0xbfb8aa3b, v8
	v_mul_f32_e32 v11, 0xbfb8aa3b, v9
	v_exp_f32_e32 v10, v10
	v_exp_f32_e32 v11, v11
	v_add_f32_e32 v4, 1.0, v4
	v_add_f32_e32 v5, 1.0, v5
	v_rcp_f32_e32 v4, v4
	v_rcp_f32_e32 v5, v5
	v_add_f32_e32 v10, 1.0, v10
	v_add_f32_e32 v11, 1.0, v11
	v_rcp_f32_e32 v10, v10
	v_rcp_f32_e32 v11, v11
	v_pk_mul_f32 v[6:7], v[14:15], v[0:1] op_sel_hi:[1,0]
	v_pk_mul_f32 v[2:3], v[4:5], v[2:3]
	v_pk_mul_f32 v[4:5], v[16:17], v[0:1] op_sel_hi:[1,0]
	v_pk_mul_f32 v[2:3], v[6:7], v[2:3]
	v_pk_mul_f32 v[6:7], v[10:11], v[8:9]
	v_cvt_pk_bf16_f32 v2, v2, v3
	v_pk_mul_f32 v[4:5], v[4:5], v[6:7]
	s_nop 0
	v_cvt_pk_bf16_f32 v3, v4, v5
	v_mov_b32_e32 v104, v2
	v_mov_b32_e32 v105, v3
	s_nop 1
	v_permlane32_swap_b32_e32 v104, v106
	v_permlane32_swap_b32_e32 v105, v107
	global_store_dwordx4 v[112:113], v[104:107], off offset:96
